# v108: v106 + the two waits that end every load segment merged into one s_waitcnt with the priority raise ahead of it
# speedup vs baseline: 1.0034x; 1.0000x over previous
; #define PG8_STAGE(bufoff, gbase, voff) do { _Pragma("unroll") for (int _i = 0; _i < 2; ++_i) \
;         __builtin_amdgcn_global_load_lds((const unsigned*)((const char*)(gbase) + (voff)[_i]), (PG8_LAS unsigned*)(lds + (bufoff) + ldsw + _i * 8192), 16, 0, 0); } while (0)
; #define PG8_LDA(dst, b, h) do { _Pragma("unroll") for (int m = 0; m < 4; ++m) _Pragma("unroll") for (int k = 0; k < 2; ++k) dst[m][k] = *(const PG8_LAS bf16x8*)(lds + PG8_SA(b, h) + aoff + m * 2048 + k * 1024); } while (0)
; #define PG8_LDB(dst, b, h) do { _Pragma("unroll") for (int n = 0; n < 2; ++n) _Pragma("unroll") for (int k = 0; k < 2; ++k) dst[n][k] = *(const PG8_LAS bf16x8*)(lds + PG8_SB(b, h) + boff + n * 2048 + k * 1024); } while (0)
; #define PG8_MMA(ai, bj, At, Bt) do { __builtin_amdgcn_s_setprio(1); _Pragma("unroll") for (int m = 0; m < 4; ++m) _Pragma("unroll") for (int n = 0; n < 2; ++n) _Pragma("unroll") for (int k = 0; k < 2; ++k) \
;         acc[ai][bj][m][n] = __builtin_amdgcn_mfma_f32_16x16x32_bf16(Bt[n][k], At[m][k], acc[ai][bj][m][n], 0, 0, 0); __builtin_amdgcn_s_setprio(0); } while (0)
; #define PG8_WAIT_V(n) asm volatile("s_waitcnt vmcnt(" #n ")" ::: "memory")
; template <class Epi, class Sched, bool ALIGN_EPI, int LMASK = -1, int LMASKB = LMASK>
; __device__ __forceinline__ void gemm_phase(PG8_LAS unsigned char* lds, const Gemm g, const Sched& S, const Epi& E) {
;     ...
;         const char* nA = has_next ? (const char*)g.A + (size_t)(nxt.pm & LMASK) * tstepA : cA; const char* nB = has_next ? (const char*)g.Bt + (size_t)nxt.pm * g.b_pm_stride + (size_t)(nxt.pn & LMASKB) * tstepB : cB;
;         for (int t = 0; t < nt; t += 2) {
;             const bool last = (t == nt - 2);
;             const char* a1 = cA + (size_t)(t + 1) * kstepA;
;             const char* a2 = last ? nA : cA + (size_t)(t + 2) * kstepA; const char* b2 = last ? nB : cB + (size_t)(t + 2) * kstepB;
;             const char* a3 = a2 + kstepA; const char* b3 = b2 + kstepB;
;             PG8_LDB(B0, 0, 0); PG8_LDB(B1, 0, 1); PG8_SCHED; PG8_LDA(At, 0, 0); PG8_STAGE(PG8_SA(1, 1), a1 + hstepA, voffA);
;             PG8_WAIT_V(8); PG8_WAIT_L(0); PG8_BAR; PG8_MMA(0, 0, At, B0); PG8_MMA(0, 1, At, B1); PG8_BAR; PG8_SCHED;
;             PG8_LDA(At, 0, 1); PG8_STAGE(PG8_SB(0, 0), b2, voffB); PG8_STAGE(PG8_SB(0, 1), b2 + hstepB, voffB); PG8_STAGE(PG8_SA(0, 0), a2, voffA);
.LBB0_206:
	s_ashr_i32 s17, s16, 31
	s_lshl_b64 s[2:3], s[16:17], 17
	s_add_u32 s20, s1, s2
	s_addc_u32 s21, s33, s3
	s_and_b64 s[2:3], s[4:5], exec
	s_cselect_b32 s29, s21, s23
	s_cselect_b32 s28, s20, s22
	s_lshl_b64 s[2:3], s[16:17], 21
	s_add_u32 s17, s36, s2
	ds_read_b128 v[2:5], v142
	ds_read_b128 v[6:9], v142 offset:1024
	ds_read_b128 v[10:13], v142 offset:2048
	ds_read_b128 v[14:17], v142 offset:3072
	ds_read_b128 v[18:21], v143
	ds_read_b128 v[22:25], v143 offset:1024
	ds_read_b128 v[26:29], v143 offset:2048
	ds_read_b128 v[30:33], v143 offset:3072
	s_addc_u32 s26, s37, s3
	s_ashr_i32 s15, s14, 31
	s_lshl_b64 s[2:3], s[14:15], 17
	s_add_u32 s2, s17, s2
	s_addc_u32 s3, s26, s3
	s_and_b64 s[26:27], s[4:5], exec
	s_cselect_b32 s27, s3, s25
	s_cselect_b32 s26, s2, s24
	s_add_u32 s34, s22, 0x1000
	s_addc_u32 s35, s23, 0
	s_add_u32 s54, s24, 0x1000
	s_addc_u32 s55, s25, 0
	s_add_u32 s30, s22, 0x1800
	s_addc_u32 s31, s23, 0
	s_add_u32 s56, s22, 0x10800
	s_addc_u32 s57, s23, 0
	s_mov_b32 m0, s50
	v_lshl_add_u64 v[66:67], s[56:57], 0, v[130:131]
	ds_read_b128 v[34:37], v144
	ds_read_b128 v[38:41], v144 offset:1024
	ds_read_b128 v[42:45], v144 offset:2048
	ds_read_b128 v[46:49], v144 offset:3072
	ds_read_b128 v[50:53], v144 offset:4096
	ds_read_b128 v[54:57], v144 offset:5120
	ds_read_b128 v[58:61], v144 offset:6144
	ds_read_b128 v[62:65], v144 offset:7168
	global_load_lds_dwordx4 v[66:67], off
	s_mov_b32 m0, s51
	v_lshl_add_u64 v[66:67], s[56:57], 0, v[132:133]
	global_load_lds_dwordx4 v[66:67], off
	s_setprio 1
	s_waitcnt vmcnt(8) lgkmcnt(0)
	s_barrier
	v_mfma_f32_16x16x32_bf16 v[66:69], v[2:5], v[34:37], 0
	v_mfma_f32_16x16x32_bf16 v[70:73], v[10:13], v[34:37], 0
	v_mfma_f32_16x16x32_bf16 v[74:77], v[2:5], v[42:45], 0
	v_mfma_f32_16x16x32_bf16 v[78:81], v[10:13], v[42:45], 0
	v_mfma_f32_16x16x32_bf16 v[82:85], v[2:5], v[50:53], 0
	v_mfma_f32_16x16x32_bf16 v[86:89], v[10:13], v[50:53], 0
	v_mfma_f32_16x16x32_bf16 v[90:93], v[2:5], v[58:61], 0
	v_mfma_f32_16x16x32_bf16 v[94:97], v[10:13], v[58:61], 0
	v_mfma_f32_16x16x32_bf16 v[66:69], v[6:9], v[38:41], v[66:69]
	v_mfma_f32_16x16x32_bf16 v[70:73], v[14:17], v[38:41], v[70:73]
	v_mfma_f32_16x16x32_bf16 v[74:77], v[6:9], v[46:49], v[74:77]
	v_mfma_f32_16x16x32_bf16 v[78:81], v[14:17], v[46:49], v[78:81]
	v_mfma_f32_16x16x32_bf16 v[82:85], v[6:9], v[54:57], v[82:85]
	v_mfma_f32_16x16x32_bf16 v[86:89], v[14:17], v[54:57], v[86:89]
	v_mfma_f32_16x16x32_bf16 v[90:93], v[6:9], v[62:65], v[90:93]
	v_mfma_f32_16x16x32_bf16 v[94:97], v[14:17], v[62:65], v[94:97]
	v_mfma_f32_16x16x32_bf16 v[98:101], v[18:21], v[34:37], 0
	v_mfma_f32_16x16x32_bf16 v[34:37], v[26:29], v[34:37], 0
	v_mfma_f32_16x16x32_bf16 v[98:101], v[22:25], v[38:41], v[98:101]
	v_mfma_f32_16x16x32_bf16 v[34:37], v[30:33], v[38:41], v[34:37]
	v_mfma_f32_16x16x32_bf16 v[38:41], v[18:21], v[42:45], 0
	v_mfma_f32_16x16x32_bf16 v[42:45], v[26:29], v[42:45], 0
	v_mfma_f32_16x16x32_bf16 v[38:41], v[22:25], v[46:49], v[38:41]
	v_mfma_f32_16x16x32_bf16 v[42:45], v[30:33], v[46:49], v[42:45]
	v_mfma_f32_16x16x32_bf16 v[46:49], v[18:21], v[50:53], 0
	v_mfma_f32_16x16x32_bf16 v[50:53], v[26:29], v[50:53], 0
	v_mfma_f32_16x16x32_bf16 v[46:49], v[22:25], v[54:57], v[46:49]
	v_mfma_f32_16x16x32_bf16 v[50:53], v[30:33], v[54:57], v[50:53]
	v_mfma_f32_16x16x32_bf16 v[54:57], v[18:21], v[58:61], 0
	v_mfma_f32_16x16x32_bf16 v[58:61], v[26:29], v[58:61], 0
	v_mfma_f32_16x16x32_bf16 v[54:57], v[22:25], v[62:65], v[54:57]
	v_mfma_f32_16x16x32_bf16 v[58:61], v[30:33], v[62:65], v[58:61]
	s_barrier
	s_setprio 0
	s_mov_b32 m0, s52
	v_lshl_add_u64 v[146:147], s[54:55], 0, v[130:131]
	s_add_i32 s15, s52, 0x2000
	ds_read_b128 v[62:65], v144 offset:16384
	ds_read_b128 v[102:105], v144 offset:17408
	ds_read_b128 v[106:109], v144 offset:18432
	ds_read_b128 v[110:113], v144 offset:19456
	ds_read_b128 v[114:117], v144 offset:20480
	ds_read_b128 v[118:121], v144 offset:21504
	ds_read_b128 v[122:125], v144 offset:22528
	ds_read_b128 v[126:129], v144 offset:23552
	global_load_lds_dwordx4 v[146:147], off
	v_lshl_add_u64 v[146:147], s[54:55], 0, v[132:133]
	s_add_u32 s54, s24, 0x11000
	s_mov_b32 m0, s15
	s_addc_u32 s55, s25, 0
	s_add_i32 s17, s48, s38
	global_load_lds_dwordx4 v[146:147], off
	s_mov_b32 m0, s17
	v_lshl_add_u64 v[146:147], s[54:55], 0, v[130:131]
	global_load_lds_dwordx4 v[146:147], off
	v_lshl_add_u64 v[146:147], s[54:55], 0, v[132:133]
	s_add_i32 s54, s17, 0x2000
	s_mov_b32 m0, s54
	s_nop 0
	global_load_lds_dwordx4 v[146:147], off
	s_mov_b32 m0, s19
	v_lshl_add_u64 v[146:147], s[34:35], 0, v[130:131]
	global_load_lds_dwordx4 v[146:147], off
	s_mov_b32 m0, s39
	v_lshl_add_u64 v[146:147], s[34:35], 0, v[132:133]
	global_load_lds_dwordx4 v[146:147], off
	s_setprio 1
	s_waitcnt vmcnt(8) lgkmcnt(0)
	s_barrier
; #define PG8_STAGE(bufoff, gbase, voff) do { _Pragma("unroll") for (int _i = 0; _i < 2; ++_i) \
;         __builtin_amdgcn_global_load_lds((const unsigned*)((const char*)(gbase) + (voff)[_i]), (PG8_LAS unsigned*)(lds + (bufoff) + ldsw + _i * 8192), 16, 0, 0); } while (0)
; #define PG8_LDA(dst, b, h) do { _Pragma("unroll") for (int m = 0; m < 4; ++m) _Pragma("unroll") for (int k = 0; k < 2; ++k) dst[m][k] = *(const PG8_LAS bf16x8*)(lds + PG8_SA(b, h) + aoff + m * 2048 + k * 1024); } while (0)
; #define PG8_LDB(dst, b, h) do { _Pragma("unroll") for (int n = 0; n < 2; ++n) _Pragma("unroll") for (int k = 0; k < 2; ++k) dst[n][k] = *(const PG8_LAS bf16x8*)(lds + PG8_SB(b, h) + boff + n * 2048 + k * 1024); } while (0)
; #define PG8_MMA(ai, bj, At, Bt) do { __builtin_amdgcn_s_setprio(1); _Pragma("unroll") for (int m = 0; m < 4; ++m) _Pragma("unroll") for (int n = 0; n < 2; ++n) _Pragma("unroll") for (int k = 0; k < 2; ++k) \
;         acc[ai][bj][m][n] = __builtin_amdgcn_mfma_f32_16x16x32_bf16(Bt[n][k], At[m][k], acc[ai][bj][m][n], 0, 0, 0); __builtin_amdgcn_s_setprio(0); } while (0)
; #define PG8_WAIT_V(n) asm volatile("s_waitcnt vmcnt(" #n ")" ::: "memory")
; #define PG8_WAIT_L(n) asm volatile("s_waitcnt lgkmcnt(" #n ")" ::: "memory")
; #define PG8_BAR __builtin_amdgcn_s_barrier()
; #define PG8_SCHED __builtin_amdgcn_sched_barrier(0)
; template <class Epi, class Sched, bool ALIGN_EPI, int LMASK = -1, int LMASKB = LMASK>
; __device__ __forceinline__ void gemm_phase(PG8_LAS unsigned char* lds, const Gemm g, const Sched& S, const Epi& E) {
;     ...
;             PG8_WAIT_V(8); PG8_WAIT_L(0); PG8_BAR; PG8_MMA(1, 0, At, B0); PG8_MMA(1, 1, At, B1); PG8_BAR; PG8_SCHED;
;             PG8_LDB(B0, 1, 0); PG8_LDB(B1, 1, 1); PG8_SCHED; PG8_LDA(At, 1, 0); PG8_STAGE(PG8_SA(0, 1), a2 + hstepA, voffA);
;             PG8_WAIT_V(8); PG8_WAIT_L(0); PG8_BAR; PG8_MMA(0, 0, At, B0); PG8_MMA(0, 1, At, B1); PG8_BAR; PG8_SCHED;
	v_mfma_f32_16x16x32_bf16 v[146:149], v[2:5], v[62:65], 0
	v_mfma_f32_16x16x32_bf16 v[154:157], v[2:5], v[106:109], 0
	v_mfma_f32_16x16x32_bf16 v[162:165], v[2:5], v[114:117], 0
	v_mfma_f32_16x16x32_bf16 v[2:5], v[2:5], v[122:125], 0
	v_mfma_f32_16x16x32_bf16 v[146:149], v[6:9], v[102:105], v[146:149]
	v_mfma_f32_16x16x32_bf16 v[154:157], v[6:9], v[110:113], v[154:157]
	v_mfma_f32_16x16x32_bf16 v[162:165], v[6:9], v[118:121], v[162:165]
	v_mfma_f32_16x16x32_bf16 v[2:5], v[6:9], v[126:129], v[2:5]
	v_mfma_f32_16x16x32_bf16 v[6:9], v[10:13], v[122:125], 0
	v_mfma_f32_16x16x32_bf16 v[150:153], v[10:13], v[62:65], 0
	v_mfma_f32_16x16x32_bf16 v[158:161], v[10:13], v[106:109], 0
	v_mfma_f32_16x16x32_bf16 v[166:169], v[10:13], v[114:117], 0
	v_mfma_f32_16x16x32_bf16 v[6:9], v[14:17], v[126:129], v[6:9]
	v_mfma_f32_16x16x32_bf16 v[150:153], v[14:17], v[102:105], v[150:153]
	v_mfma_f32_16x16x32_bf16 v[158:161], v[14:17], v[110:113], v[158:161]
	v_mfma_f32_16x16x32_bf16 v[166:169], v[14:17], v[118:121], v[166:169]
	v_mfma_f32_16x16x32_bf16 v[10:13], v[18:21], v[62:65], 0
	v_mfma_f32_16x16x32_bf16 v[14:17], v[26:29], v[62:65], 0
	v_mfma_f32_16x16x32_bf16 v[10:13], v[22:25], v[102:105], v[10:13]
	v_mfma_f32_16x16x32_bf16 v[14:17], v[30:33], v[102:105], v[14:17]
	v_mfma_f32_16x16x32_bf16 v[62:65], v[18:21], v[106:109], 0
	v_mfma_f32_16x16x32_bf16 v[102:105], v[26:29], v[106:109], 0
	v_mfma_f32_16x16x32_bf16 v[106:109], v[18:21], v[114:117], 0
	v_mfma_f32_16x16x32_bf16 v[18:21], v[18:21], v[122:125], 0
	v_mfma_f32_16x16x32_bf16 v[62:65], v[22:25], v[110:113], v[62:65]
	v_mfma_f32_16x16x32_bf16 v[102:105], v[30:33], v[110:113], v[102:105]
	v_mfma_f32_16x16x32_bf16 v[106:109], v[22:25], v[118:121], v[106:109]
	v_mfma_f32_16x16x32_bf16 v[110:113], v[26:29], v[114:117], 0
	v_mfma_f32_16x16x32_bf16 v[18:21], v[22:25], v[126:129], v[18:21]
	v_mfma_f32_16x16x32_bf16 v[22:25], v[26:29], v[122:125], 0
	v_mfma_f32_16x16x32_bf16 v[110:113], v[30:33], v[118:121], v[110:113]
	v_mfma_f32_16x16x32_bf16 v[22:25], v[30:33], v[126:129], v[22:25]
	s_barrier
	s_setprio 0
	s_add_i32 s55, 0, 0x18000
	s_add_i32 s58, 0, 0x1c000
	v_add_u32_e32 v134, s55, v1
	v_add_u32_e32 v222, s58, v1
	ds_read_b128 v[26:29], v134
	ds_read_b128 v[30:33], v134 offset:1024
	ds_read_b128 v[114:117], v134 offset:2048
	ds_read_b128 v[118:121], v134 offset:3072
	ds_read_b128 v[122:125], v222
	ds_read_b128 v[126:129], v222 offset:1024
	ds_read_b128 v[170:173], v222 offset:2048
	ds_read_b128 v[174:177], v222 offset:3072
	s_add_u32 s34, s22, 0x11000
	s_addc_u32 s35, s23, 0
	s_mov_b32 m0, s40
	v_lshl_add_u64 v[210:211], s[34:35], 0, v[130:131]
	ds_read_b128 v[178:181], v144 offset:32768
	ds_read_b128 v[182:185], v144 offset:33792
	ds_read_b128 v[186:189], v144 offset:34816
	ds_read_b128 v[190:193], v144 offset:35840
	ds_read_b128 v[194:197], v144 offset:36864
	ds_read_b128 v[198:201], v144 offset:37888
	ds_read_b128 v[202:205], v144 offset:38912
	ds_read_b128 v[206:209], v144 offset:39936
	global_load_lds_dwordx4 v[210:211], off
	s_mov_b32 m0, s41
	v_lshl_add_u64 v[210:211], s[34:35], 0, v[132:133]
	global_load_lds_dwordx4 v[210:211], off
	s_setprio 1
	s_waitcnt vmcnt(8) lgkmcnt(0)
	s_barrier
	v_mfma_f32_16x16x32_bf16 v[66:69], v[26:29], v[178:181], v[66:69]
	v_mfma_f32_16x16x32_bf16 v[70:73], v[114:117], v[178:181], v[70:73]
	v_mfma_f32_16x16x32_bf16 v[74:77], v[26:29], v[186:189], v[74:77]
	v_mfma_f32_16x16x32_bf16 v[78:81], v[114:117], v[186:189], v[78:81]
	v_mfma_f32_16x16x32_bf16 v[82:85], v[26:29], v[194:197], v[82:85]
	v_mfma_f32_16x16x32_bf16 v[86:89], v[114:117], v[194:197], v[86:89]
	v_mfma_f32_16x16x32_bf16 v[90:93], v[26:29], v[202:205], v[90:93]
	v_mfma_f32_16x16x32_bf16 v[94:97], v[114:117], v[202:205], v[94:97]
	v_mfma_f32_16x16x32_bf16 v[66:69], v[30:33], v[182:185], v[66:69]
	v_mfma_f32_16x16x32_bf16 v[70:73], v[118:121], v[182:185], v[70:73]
	v_mfma_f32_16x16x32_bf16 v[74:77], v[30:33], v[190:193], v[74:77]
	v_mfma_f32_16x16x32_bf16 v[78:81], v[118:121], v[190:193], v[78:81]
	v_mfma_f32_16x16x32_bf16 v[82:85], v[30:33], v[198:201], v[82:85]
	v_mfma_f32_16x16x32_bf16 v[86:89], v[118:121], v[198:201], v[86:89]
	v_mfma_f32_16x16x32_bf16 v[90:93], v[30:33], v[206:209], v[90:93]
	v_mfma_f32_16x16x32_bf16 v[94:97], v[118:121], v[206:209], v[94:97]
	v_mfma_f32_16x16x32_bf16 v[98:101], v[122:125], v[178:181], v[98:101]
	v_mfma_f32_16x16x32_bf16 v[34:37], v[170:173], v[178:181], v[34:37]
	v_mfma_f32_16x16x32_bf16 v[38:41], v[122:125], v[186:189], v[38:41]
	v_mfma_f32_16x16x32_bf16 v[42:45], v[170:173], v[186:189], v[42:45]
	v_mfma_f32_16x16x32_bf16 v[46:49], v[122:125], v[194:197], v[46:49]
	v_mfma_f32_16x16x32_bf16 v[50:53], v[170:173], v[194:197], v[50:53]
	v_mfma_f32_16x16x32_bf16 v[54:57], v[122:125], v[202:205], v[54:57]
	v_mfma_f32_16x16x32_bf16 v[58:61], v[170:173], v[202:205], v[58:61]
	v_mfma_f32_16x16x32_bf16 v[98:101], v[126:129], v[182:185], v[98:101]
	v_mfma_f32_16x16x32_bf16 v[34:37], v[174:177], v[182:185], v[34:37]
	v_mfma_f32_16x16x32_bf16 v[38:41], v[126:129], v[190:193], v[38:41]
	v_mfma_f32_16x16x32_bf16 v[42:45], v[174:177], v[190:193], v[42:45]
	v_mfma_f32_16x16x32_bf16 v[46:49], v[126:129], v[198:201], v[46:49]
	v_mfma_f32_16x16x32_bf16 v[50:53], v[174:177], v[198:201], v[50:53]
	v_mfma_f32_16x16x32_bf16 v[54:57], v[126:129], v[206:209], v[54:57]
	v_mfma_f32_16x16x32_bf16 v[58:61], v[174:177], v[206:209], v[58:61]
	s_barrier
; #define PG8_STAGE(bufoff, gbase, voff) do { _Pragma("unroll") for (int _i = 0; _i < 2; ++_i) \
;         __builtin_amdgcn_global_load_lds((const unsigned*)((const char*)(gbase) + (voff)[_i]), (PG8_LAS unsigned*)(lds + (bufoff) + ldsw + _i * 8192), 16, 0, 0); } while (0)
; #define PG8_LDA(dst, b, h) do { _Pragma("unroll") for (int m = 0; m < 4; ++m) _Pragma("unroll") for (int k = 0; k < 2; ++k) dst[m][k] = *(const PG8_LAS bf16x8*)(lds + PG8_SA(b, h) + aoff + m * 2048 + k * 1024); } while (0)
; #define PG8_LDB(dst, b, h) do { _Pragma("unroll") for (int n = 0; n < 2; ++n) _Pragma("unroll") for (int k = 0; k < 2; ++k) dst[n][k] = *(const PG8_LAS bf16x8*)(lds + PG8_SB(b, h) + boff + n * 2048 + k * 1024); } while (0)
; #define PG8_MMA(ai, bj, At, Bt) do { __builtin_amdgcn_s_setprio(1); _Pragma("unroll") for (int m = 0; m < 4; ++m) _Pragma("unroll") for (int n = 0; n < 2; ++n) _Pragma("unroll") for (int k = 0; k < 2; ++k) \
;         acc[ai][bj][m][n] = __builtin_amdgcn_mfma_f32_16x16x32_bf16(Bt[n][k], At[m][k], acc[ai][bj][m][n], 0, 0, 0); __builtin_amdgcn_s_setprio(0); } while (0)
; #define PG8_WAIT_V(n) asm volatile("s_waitcnt vmcnt(" #n ")" ::: "memory")
; #define PG8_WAIT_L(n) asm volatile("s_waitcnt lgkmcnt(" #n ")" ::: "memory")
; #define PG8_BAR __builtin_amdgcn_s_barrier()
; #define PG8_SCHED __builtin_amdgcn_sched_barrier(0)
; template <class Epi, class Sched, bool ALIGN_EPI, int LMASK = -1, int LMASKB = LMASK>
; __device__ __forceinline__ void gemm_phase(PG8_LAS unsigned char* lds, const Gemm g, const Sched& S, const Epi& E) {
;     ...
;             PG8_LDB(B0, 0, 0); PG8_LDB(B1, 0, 1); PG8_SCHED; PG8_LDA(At, 0, 0); PG8_STAGE(PG8_SA(1, 1), a1 + hstepA, voffA);
;     ...
;             PG8_LDA(At, 1, 1); PG8_STAGE(PG8_SB(1, 0), b3, voffB); PG8_STAGE(PG8_SB(1, 1), b3 + hstepB, voffB); PG8_STAGE(PG8_SA(1, 0), a3, voffA);
;             PG8_WAIT_V(8); PG8_WAIT_L(0); PG8_BAR; PG8_MMA(1, 0, At, B0); PG8_MMA(1, 1, At, B1); PG8_BAR; PG8_SCHED;
	s_setprio 0
	s_add_u32 s56, s24, 0x1800
	s_addc_u32 s57, s25, 0
	s_add_i32 s35, s55, s38
	v_lshl_add_u64 v[210:211], s[56:57], 0, v[130:131]
	s_mov_b32 m0, s35
	s_add_i32 s34, s35, 0x2000
	ds_read_b128 v[178:181], v144 offset:49152
	ds_read_b128 v[182:185], v144 offset:50176
	ds_read_b128 v[186:189], v144 offset:51200
	ds_read_b128 v[190:193], v144 offset:52224
	ds_read_b128 v[194:197], v144 offset:53248
	ds_read_b128 v[198:201], v144 offset:54272
	ds_read_b128 v[202:205], v144 offset:55296
	ds_read_b128 v[206:209], v144 offset:56320
	global_load_lds_dwordx4 v[210:211], off
	v_lshl_add_u64 v[210:211], s[56:57], 0, v[132:133]
	s_add_u32 s56, s24, 0x11800
	s_mov_b32 m0, s34
	s_addc_u32 s57, s25, 0
	s_add_i32 s24, s58, s38
	global_load_lds_dwordx4 v[210:211], off
	v_lshl_add_u64 v[210:211], s[56:57], 0, v[130:131]
	s_mov_b32 m0, s24
	s_add_i32 s25, s24, 0x2000
	global_load_lds_dwordx4 v[210:211], off
	s_mov_b32 m0, s25
	v_lshl_add_u64 v[210:211], s[56:57], 0, v[132:133]
	global_load_lds_dwordx4 v[210:211], off
	s_mov_b32 m0, s44
	v_lshl_add_u64 v[210:211], s[30:31], 0, v[130:131]
	global_load_lds_dwordx4 v[210:211], off
	s_mov_b32 m0, s45
	v_lshl_add_u64 v[210:211], s[30:31], 0, v[132:133]
	global_load_lds_dwordx4 v[210:211], off
	s_setprio 1
	s_waitcnt vmcnt(8) lgkmcnt(0)
	s_barrier
	v_mfma_f32_16x16x32_bf16 v[2:5], v[26:29], v[202:205], v[2:5]
	v_mfma_f32_16x16x32_bf16 v[6:9], v[114:117], v[202:205], v[6:9]
	v_mfma_f32_16x16x32_bf16 v[146:149], v[26:29], v[178:181], v[146:149]
	v_mfma_f32_16x16x32_bf16 v[150:153], v[114:117], v[178:181], v[150:153]
	v_mfma_f32_16x16x32_bf16 v[154:157], v[26:29], v[186:189], v[154:157]
	v_mfma_f32_16x16x32_bf16 v[158:161], v[114:117], v[186:189], v[158:161]
	v_mfma_f32_16x16x32_bf16 v[162:165], v[26:29], v[194:197], v[162:165]
	v_mfma_f32_16x16x32_bf16 v[166:169], v[114:117], v[194:197], v[166:169]
	v_mfma_f32_16x16x32_bf16 v[2:5], v[30:33], v[206:209], v[2:5]
	v_mfma_f32_16x16x32_bf16 v[6:9], v[118:121], v[206:209], v[6:9]
	v_mfma_f32_16x16x32_bf16 v[146:149], v[30:33], v[182:185], v[146:149]
	v_mfma_f32_16x16x32_bf16 v[150:153], v[118:121], v[182:185], v[150:153]
	v_mfma_f32_16x16x32_bf16 v[154:157], v[30:33], v[190:193], v[154:157]
	v_mfma_f32_16x16x32_bf16 v[158:161], v[118:121], v[190:193], v[158:161]
	v_mfma_f32_16x16x32_bf16 v[162:165], v[30:33], v[198:201], v[162:165]
	v_mfma_f32_16x16x32_bf16 v[166:169], v[118:121], v[198:201], v[166:169]
	v_mfma_f32_16x16x32_bf16 v[10:13], v[122:125], v[178:181], v[10:13]
	v_mfma_f32_16x16x32_bf16 v[14:17], v[170:173], v[178:181], v[14:17]
	v_mfma_f32_16x16x32_bf16 v[26:29], v[122:125], v[186:189], v[62:65]
	v_mfma_f32_16x16x32_bf16 v[30:33], v[170:173], v[186:189], v[102:105]
	v_mfma_f32_16x16x32_bf16 v[62:65], v[122:125], v[194:197], v[106:109]
	v_mfma_f32_16x16x32_bf16 v[102:105], v[170:173], v[194:197], v[110:113]
	v_mfma_f32_16x16x32_bf16 v[18:21], v[122:125], v[202:205], v[18:21]
	v_mfma_f32_16x16x32_bf16 v[22:25], v[170:173], v[202:205], v[22:25]
	v_mfma_f32_16x16x32_bf16 v[10:13], v[126:129], v[182:185], v[10:13]
	v_mfma_f32_16x16x32_bf16 v[14:17], v[174:177], v[182:185], v[14:17]
	v_mfma_f32_16x16x32_bf16 v[26:29], v[126:129], v[190:193], v[26:29]
	v_mfma_f32_16x16x32_bf16 v[30:33], v[174:177], v[190:193], v[30:33]
	v_mfma_f32_16x16x32_bf16 v[62:65], v[126:129], v[198:201], v[62:65]
	v_mfma_f32_16x16x32_bf16 v[102:105], v[174:177], v[198:201], v[102:105]
	v_mfma_f32_16x16x32_bf16 v[18:21], v[126:129], v[206:209], v[18:21]
	v_mfma_f32_16x16x32_bf16 v[22:25], v[174:177], v[206:209], v[22:25]
	s_barrier
	s_setprio 0
	ds_read_b128 v[106:109], v142
	ds_read_b128 v[110:113], v142 offset:1024
	ds_read_b128 v[114:117], v142 offset:2048
	ds_read_b128 v[118:121], v142 offset:3072
	ds_read_b128 v[122:125], v143
	ds_read_b128 v[126:129], v143 offset:1024
	ds_read_b128 v[170:173], v143 offset:2048
	ds_read_b128 v[174:177], v143 offset:3072
	s_add_u32 s22, s22, 0x11800
	s_addc_u32 s23, s23, 0
	s_mov_b32 m0, s50
	v_lshl_add_u64 v[210:211], s[22:23], 0, v[130:131]
	ds_read_b128 v[178:181], v144
	ds_read_b128 v[182:185], v144 offset:1024
	ds_read_b128 v[186:189], v144 offset:2048
	ds_read_b128 v[190:193], v144 offset:3072
	ds_read_b128 v[194:197], v144 offset:4096
	ds_read_b128 v[198:201], v144 offset:5120
	ds_read_b128 v[202:205], v144 offset:6144
	ds_read_b128 v[206:209], v144 offset:7168
	global_load_lds_dwordx4 v[210:211], off
	s_mov_b32 m0, s51
	v_lshl_add_u64 v[210:211], s[22:23], 0, v[132:133]
	global_load_lds_dwordx4 v[210:211], off
	s_setprio 1
	s_waitcnt vmcnt(8) lgkmcnt(0)
	s_barrier
; #define PG8_STAGE(bufoff, gbase, voff) do { _Pragma("unroll") for (int _i = 0; _i < 2; ++_i) \
;         __builtin_amdgcn_global_load_lds((const unsigned*)((const char*)(gbase) + (voff)[_i]), (PG8_LAS unsigned*)(lds + (bufoff) + ldsw + _i * 8192), 16, 0, 0); } while (0)
; #define PG8_LDA(dst, b, h) do { _Pragma("unroll") for (int m = 0; m < 4; ++m) _Pragma("unroll") for (int k = 0; k < 2; ++k) dst[m][k] = *(const PG8_LAS bf16x8*)(lds + PG8_SA(b, h) + aoff + m * 2048 + k * 1024); } while (0)
; #define PG8_MMA(ai, bj, At, Bt) do { __builtin_amdgcn_s_setprio(1); _Pragma("unroll") for (int m = 0; m < 4; ++m) _Pragma("unroll") for (int n = 0; n < 2; ++n) _Pragma("unroll") for (int k = 0; k < 2; ++k) \
;         acc[ai][bj][m][n] = __builtin_amdgcn_mfma_f32_16x16x32_bf16(Bt[n][k], At[m][k], acc[ai][bj][m][n], 0, 0, 0); __builtin_amdgcn_s_setprio(0); } while (0)
; #define PG8_WAIT_V(n) asm volatile("s_waitcnt vmcnt(" #n ")" ::: "memory")
; #define PG8_WAIT_L(n) asm volatile("s_waitcnt lgkmcnt(" #n ")" ::: "memory")
; #define PG8_BAR __builtin_amdgcn_s_barrier()
; #define PG8_SCHED __builtin_amdgcn_sched_barrier(0)
; template <class Epi, class Sched, bool ALIGN_EPI, int LMASK = -1, int LMASKB = LMASK>
; __device__ __forceinline__ void gemm_phase(PG8_LAS unsigned char* lds, const Gemm g, const Sched& S, const Epi& E) {
;     ...
;             PG8_WAIT_V(8); PG8_WAIT_L(0); PG8_BAR; PG8_MMA(0, 0, At, B0); PG8_MMA(0, 1, At, B1); PG8_BAR; PG8_SCHED;
;             PG8_LDA(At, 0, 1); PG8_STAGE(PG8_SB(0, 0), b2, voffB); PG8_STAGE(PG8_SB(0, 1), b2 + hstepB, voffB); PG8_STAGE(PG8_SA(0, 0), a2, voffA);
;             PG8_WAIT_V(8); PG8_WAIT_L(0); PG8_BAR; PG8_MMA(1, 0, At, B0); PG8_MMA(1, 1, At, B1); PG8_BAR; PG8_SCHED;
	v_mfma_f32_16x16x32_bf16 v[66:69], v[106:109], v[178:181], v[66:69]
	v_mfma_f32_16x16x32_bf16 v[70:73], v[114:117], v[178:181], v[70:73]
	v_mfma_f32_16x16x32_bf16 v[74:77], v[106:109], v[186:189], v[74:77]
	v_mfma_f32_16x16x32_bf16 v[78:81], v[114:117], v[186:189], v[78:81]
	v_mfma_f32_16x16x32_bf16 v[82:85], v[106:109], v[194:197], v[82:85]
	v_mfma_f32_16x16x32_bf16 v[86:89], v[114:117], v[194:197], v[86:89]
	v_mfma_f32_16x16x32_bf16 v[90:93], v[106:109], v[202:205], v[90:93]
	v_mfma_f32_16x16x32_bf16 v[94:97], v[114:117], v[202:205], v[94:97]
	v_mfma_f32_16x16x32_bf16 v[66:69], v[110:113], v[182:185], v[66:69]
	v_mfma_f32_16x16x32_bf16 v[70:73], v[118:121], v[182:185], v[70:73]
	v_mfma_f32_16x16x32_bf16 v[74:77], v[110:113], v[190:193], v[74:77]
	v_mfma_f32_16x16x32_bf16 v[78:81], v[118:121], v[190:193], v[78:81]
	v_mfma_f32_16x16x32_bf16 v[82:85], v[110:113], v[198:201], v[82:85]
	v_mfma_f32_16x16x32_bf16 v[86:89], v[118:121], v[198:201], v[86:89]
	v_mfma_f32_16x16x32_bf16 v[90:93], v[110:113], v[206:209], v[90:93]
	v_mfma_f32_16x16x32_bf16 v[94:97], v[118:121], v[206:209], v[94:97]
	v_mfma_f32_16x16x32_bf16 v[34:37], v[170:173], v[178:181], v[34:37]
	v_mfma_f32_16x16x32_bf16 v[98:101], v[122:125], v[178:181], v[98:101]
	v_mfma_f32_16x16x32_bf16 v[178:181], v[174:177], v[182:185], v[34:37]
	v_mfma_f32_16x16x32_bf16 v[34:37], v[122:125], v[186:189], v[38:41]
	v_mfma_f32_16x16x32_bf16 v[210:213], v[126:129], v[182:185], v[98:101]
	v_mfma_f32_16x16x32_bf16 v[182:185], v[126:129], v[190:193], v[34:37]
	v_mfma_f32_16x16x32_bf16 v[34:37], v[170:173], v[186:189], v[42:45]
	v_mfma_f32_16x16x32_bf16 v[42:45], v[174:177], v[190:193], v[34:37]
	v_mfma_f32_16x16x32_bf16 v[34:37], v[122:125], v[194:197], v[46:49]
	v_mfma_f32_16x16x32_bf16 v[46:49], v[126:129], v[198:201], v[34:37]
	v_mfma_f32_16x16x32_bf16 v[34:37], v[170:173], v[194:197], v[50:53]
	v_mfma_f32_16x16x32_bf16 v[50:53], v[174:177], v[198:201], v[34:37]
	v_mfma_f32_16x16x32_bf16 v[34:37], v[122:125], v[202:205], v[54:57]
	v_mfma_f32_16x16x32_bf16 v[54:57], v[126:129], v[206:209], v[34:37]
	v_mfma_f32_16x16x32_bf16 v[34:37], v[170:173], v[202:205], v[58:61]
	v_mfma_f32_16x16x32_bf16 v[58:61], v[174:177], v[206:209], v[34:37]
	s_barrier
	s_setprio 0
	s_mov_b32 m0, s52
	v_lshl_add_u64 v[246:247], s[26:27], 0, v[130:131]
	s_add_u32 s22, s26, 0x10000
	s_nop 1
	ds_read_b128 v[34:37], v144 offset:16384
	ds_read_b128 v[38:41], v144 offset:17408
	ds_read_b128 v[98:101], v144 offset:18432
	ds_read_b128 v[186:189], v144 offset:19456
	ds_read_b128 v[190:193], v144 offset:20480
	ds_read_b128 v[194:197], v144 offset:21504
	ds_read_b128 v[198:201], v144 offset:22528
	ds_read_b128 v[202:205], v144 offset:23552
	global_load_lds_dwordx4 v[246:247], off
	v_lshl_add_u64 v[248:249], s[26:27], 0, v[132:133]
	s_mov_b32 m0, s15
	s_addc_u32 s23, s27, 0
	global_load_lds_dwordx4 v[248:249], off
	v_lshl_add_u64 v[206:207], s[22:23], 0, v[130:131]
	s_mov_b32 m0, s17
	v_lshl_add_u64 v[250:251], s[28:29], 0, v[130:131]
	global_load_lds_dwordx4 v[206:207], off
	v_lshl_add_u64 v[206:207], s[22:23], 0, v[132:133]
	s_mov_b32 m0, s54
	v_lshl_add_u64 v[252:253], s[28:29], 0, v[132:133]
	global_load_lds_dwordx4 v[206:207], off
	s_mov_b32 m0, s19
	s_nop 0
	global_load_lds_dwordx4 v[250:251], off
	s_mov_b32 m0, s39
	s_nop 0
	global_load_lds_dwordx4 v[252:253], off
	s_setprio 1
	s_waitcnt vmcnt(8) lgkmcnt(0)
	s_barrier
	v_mfma_f32_16x16x32_bf16 v[2:5], v[106:109], v[198:201], v[2:5]
	v_mfma_f32_16x16x32_bf16 v[6:9], v[114:117], v[198:201], v[6:9]
	v_mfma_f32_16x16x32_bf16 v[146:149], v[106:109], v[34:37], v[146:149]
	v_mfma_f32_16x16x32_bf16 v[150:153], v[114:117], v[34:37], v[150:153]
	v_mfma_f32_16x16x32_bf16 v[154:157], v[106:109], v[98:101], v[154:157]
	v_mfma_f32_16x16x32_bf16 v[158:161], v[114:117], v[98:101], v[158:161]
	v_mfma_f32_16x16x32_bf16 v[162:165], v[106:109], v[190:193], v[162:165]
	v_mfma_f32_16x16x32_bf16 v[166:169], v[114:117], v[190:193], v[166:169]
	v_mfma_f32_16x16x32_bf16 v[2:5], v[110:113], v[202:205], v[2:5]
	v_mfma_f32_16x16x32_bf16 v[6:9], v[118:121], v[202:205], v[6:9]
	v_mfma_f32_16x16x32_bf16 v[146:149], v[110:113], v[38:41], v[146:149]
	v_mfma_f32_16x16x32_bf16 v[150:153], v[118:121], v[38:41], v[150:153]
	v_mfma_f32_16x16x32_bf16 v[154:157], v[110:113], v[186:189], v[154:157]
	v_mfma_f32_16x16x32_bf16 v[158:161], v[118:121], v[186:189], v[158:161]
	v_mfma_f32_16x16x32_bf16 v[162:165], v[110:113], v[194:197], v[162:165]
	v_mfma_f32_16x16x32_bf16 v[166:169], v[118:121], v[194:197], v[166:169]
	v_mfma_f32_16x16x32_bf16 v[10:13], v[122:125], v[34:37], v[10:13]
	v_mfma_f32_16x16x32_bf16 v[14:17], v[170:173], v[34:37], v[14:17]
	v_mfma_f32_16x16x32_bf16 v[26:29], v[122:125], v[98:101], v[26:29]
	v_mfma_f32_16x16x32_bf16 v[30:33], v[170:173], v[98:101], v[30:33]
	v_mfma_f32_16x16x32_bf16 v[34:37], v[122:125], v[190:193], v[62:65]
	v_mfma_f32_16x16x32_bf16 v[26:29], v[126:129], v[186:189], v[26:29]
	v_mfma_f32_16x16x32_bf16 v[30:33], v[174:177], v[186:189], v[30:33]
	v_mfma_f32_16x16x32_bf16 v[186:189], v[126:129], v[194:197], v[34:37]
	v_mfma_f32_16x16x32_bf16 v[34:37], v[170:173], v[190:193], v[102:105]
	v_mfma_f32_16x16x32_bf16 v[18:21], v[122:125], v[198:201], v[18:21]
	v_mfma_f32_16x16x32_bf16 v[10:13], v[126:129], v[38:41], v[10:13]
	v_mfma_f32_16x16x32_bf16 v[14:17], v[174:177], v[38:41], v[14:17]
	v_mfma_f32_16x16x32_bf16 v[190:193], v[174:177], v[194:197], v[34:37]
	v_mfma_f32_16x16x32_bf16 v[194:197], v[126:129], v[202:205], v[18:21]
	v_mfma_f32_16x16x32_bf16 v[18:21], v[170:173], v[198:201], v[22:25]
	v_mfma_f32_16x16x32_bf16 v[170:173], v[174:177], v[202:205], v[18:21]
	s_barrier
; #define PG8_STAGE(bufoff, gbase, voff) do { _Pragma("unroll") for (int _i = 0; _i < 2; ++_i) \
;         __builtin_amdgcn_global_load_lds((const unsigned*)((const char*)(gbase) + (voff)[_i]), (PG8_LAS unsigned*)(lds + (bufoff) + ldsw + _i * 8192), 16, 0, 0); } while (0)
; #define PG8_LDA(dst, b, h) do { _Pragma("unroll") for (int m = 0; m < 4; ++m) _Pragma("unroll") for (int k = 0; k < 2; ++k) dst[m][k] = *(const PG8_LAS bf16x8*)(lds + PG8_SA(b, h) + aoff + m * 2048 + k * 1024); } while (0)
; #define PG8_LDB(dst, b, h) do { _Pragma("unroll") for (int n = 0; n < 2; ++n) _Pragma("unroll") for (int k = 0; k < 2; ++k) dst[n][k] = *(const PG8_LAS bf16x8*)(lds + PG8_SB(b, h) + boff + n * 2048 + k * 1024); } while (0)
; #define PG8_MMA(ai, bj, At, Bt) do { __builtin_amdgcn_s_setprio(1); _Pragma("unroll") for (int m = 0; m < 4; ++m) _Pragma("unroll") for (int n = 0; n < 2; ++n) _Pragma("unroll") for (int k = 0; k < 2; ++k) \
;         acc[ai][bj][m][n] = __builtin_amdgcn_mfma_f32_16x16x32_bf16(Bt[n][k], At[m][k], acc[ai][bj][m][n], 0, 0, 0); __builtin_amdgcn_s_setprio(0); } while (0)
; #define PG8_WAIT_V(n) asm volatile("s_waitcnt vmcnt(" #n ")" ::: "memory")
; #define PG8_WAIT_L(n) asm volatile("s_waitcnt lgkmcnt(" #n ")" ::: "memory")
; #define PG8_BAR __builtin_amdgcn_s_barrier()
; #define PG8_SCHED __builtin_amdgcn_sched_barrier(0)
; template <class Epi, class Sched, bool ALIGN_EPI, int LMASK = -1, int LMASKB = LMASK>
; __device__ __forceinline__ void gemm_phase(PG8_LAS unsigned char* lds, const Gemm g, const Sched& S, const Epi& E) {
;     ...
;             PG8_LDB(B0, 1, 0); PG8_LDB(B1, 1, 1); PG8_SCHED; PG8_LDA(At, 1, 0); PG8_STAGE(PG8_SA(0, 1), a2 + hstepA, voffA);
;             PG8_WAIT_V(8); PG8_WAIT_L(0); PG8_BAR; PG8_MMA(0, 0, At, B0); PG8_MMA(0, 1, At, B1); PG8_BAR; PG8_SCHED;
;             PG8_LDA(At, 1, 1); PG8_STAGE(PG8_SB(1, 0), b3, voffB); PG8_STAGE(PG8_SB(1, 1), b3 + hstepB, voffB); PG8_STAGE(PG8_SA(1, 0), a3, voffA);
;             PG8_WAIT_V(8); PG8_WAIT_L(0); PG8_BAR; PG8_MMA(1, 0, At, B0); PG8_MMA(1, 1, At, B1); PG8_BAR; PG8_SCHED;
;         }
;         if constexpr (ALIGN_EPI) { if (wr == 0) PG8_BAR; }
	s_setprio 0
	ds_read_b128 v[62:65], v134
	ds_read_b128 v[174:177], v134 offset:1024
	ds_read_b128 v[198:201], v134 offset:2048
	ds_read_b128 v[202:205], v134 offset:3072
	ds_read_b128 v[206:209], v222
	ds_read_b128 v[214:217], v222 offset:1024
	ds_read_b128 v[218:221], v222 offset:2048
	ds_read_b128 v[222:225], v222 offset:3072
	s_add_u32 s22, s28, 0x10000
	s_addc_u32 s23, s29, 0
	s_mov_b32 m0, s40
	v_lshl_add_u64 v[34:35], s[22:23], 0, v[130:131]
	ds_read_b128 v[18:21], v144 offset:32768
	ds_read_b128 v[22:25], v144 offset:33792
	ds_read_b128 v[110:113], v144 offset:34816
	ds_read_b128 v[226:229], v144 offset:35840
	ds_read_b128 v[230:233], v144 offset:36864
	ds_read_b128 v[234:237], v144 offset:37888
	ds_read_b128 v[238:241], v144 offset:38912
	ds_read_b128 v[242:245], v144 offset:39936
	global_load_lds_dwordx4 v[34:35], off
	s_mov_b32 m0, s41
	v_lshl_add_u64 v[34:35], s[22:23], 0, v[132:133]
	global_load_lds_dwordx4 v[34:35], off
	s_setprio 1
	s_waitcnt vmcnt(8) lgkmcnt(0)
	s_barrier
	v_mfma_f32_16x16x32_bf16 v[34:37], v[62:65], v[18:21], v[66:69]
	v_mfma_f32_16x16x32_bf16 v[114:117], v[174:177], v[22:25], v[34:37]
	v_mfma_f32_16x16x32_bf16 v[34:37], v[198:201], v[18:21], v[70:73]
	v_mfma_f32_16x16x32_bf16 v[118:121], v[202:205], v[22:25], v[34:37]
	v_mfma_f32_16x16x32_bf16 v[34:37], v[62:65], v[110:113], v[74:77]
	v_mfma_f32_16x16x32_bf16 v[98:101], v[174:177], v[226:229], v[34:37]
	v_mfma_f32_16x16x32_bf16 v[34:37], v[198:201], v[110:113], v[78:81]
	v_mfma_f32_16x16x32_bf16 v[102:105], v[202:205], v[226:229], v[34:37]
	v_mfma_f32_16x16x32_bf16 v[34:37], v[62:65], v[230:233], v[82:85]
	v_mfma_f32_16x16x32_bf16 v[66:69], v[174:177], v[234:237], v[34:37]
	v_mfma_f32_16x16x32_bf16 v[34:37], v[198:201], v[230:233], v[86:89]
	v_mfma_f32_16x16x32_bf16 v[70:73], v[202:205], v[234:237], v[34:37]
	v_mfma_f32_16x16x32_bf16 v[34:37], v[62:65], v[238:241], v[90:93]
	v_mfma_f32_16x16x32_bf16 v[38:41], v[198:201], v[238:241], v[94:97]
	v_mfma_f32_16x16x32_bf16 v[34:37], v[174:177], v[242:245], v[34:37]
	v_mfma_f32_16x16x32_bf16 v[38:41], v[202:205], v[242:245], v[38:41]
	v_mfma_f32_16x16x32_bf16 v[74:77], v[206:209], v[18:21], v[210:213]
	v_mfma_f32_16x16x32_bf16 v[18:21], v[218:221], v[18:21], v[178:181]
	v_mfma_f32_16x16x32_bf16 v[126:129], v[222:225], v[22:25], v[18:21]
	v_mfma_f32_16x16x32_bf16 v[18:21], v[206:209], v[110:113], v[182:185]
	v_mfma_f32_16x16x32_bf16 v[106:109], v[214:217], v[226:229], v[18:21]
	v_mfma_f32_16x16x32_bf16 v[18:21], v[218:221], v[110:113], v[42:45]
	v_mfma_f32_16x16x32_bf16 v[110:113], v[222:225], v[226:229], v[18:21]
	v_mfma_f32_16x16x32_bf16 v[18:21], v[206:209], v[230:233], v[46:49]
	v_mfma_f32_16x16x32_bf16 v[122:125], v[214:217], v[22:25], v[74:77]
	v_mfma_f32_16x16x32_bf16 v[74:77], v[214:217], v[234:237], v[18:21]
	v_mfma_f32_16x16x32_bf16 v[18:21], v[218:221], v[230:233], v[50:53]
	v_mfma_f32_16x16x32_bf16 v[78:81], v[222:225], v[234:237], v[18:21]
	v_mfma_f32_16x16x32_bf16 v[18:21], v[206:209], v[238:241], v[54:57]
	v_mfma_f32_16x16x32_bf16 v[42:45], v[214:217], v[242:245], v[18:21]
	v_mfma_f32_16x16x32_bf16 v[18:21], v[218:221], v[238:241], v[58:61]
	v_mfma_f32_16x16x32_bf16 v[46:49], v[222:225], v[242:245], v[18:21]
	s_barrier
	s_setprio 0
	s_mov_b32 m0, s35
	s_nop 3
	v_lshl_add_u64 v[18:19], v[246:247], 0, s[8:9]
	s_add_u32 s22, s26, 0x10800
	ds_read_b128 v[58:61], v144 offset:49152
	ds_read_b128 v[94:97], v144 offset:50176
	ds_read_b128 v[178:181], v144 offset:51200
	ds_read_b128 v[182:185], v144 offset:52224
	ds_read_b128 v[210:213], v144 offset:53248
	ds_read_b128 v[226:229], v144 offset:54272
	ds_read_b128 v[230:233], v144 offset:55296
	ds_read_b128 v[234:237], v144 offset:56320
	global_load_lds_dwordx4 v[18:19], off
	v_lshl_add_u64 v[18:19], v[248:249], 0, s[8:9]
	s_mov_b32 m0, s34
	s_addc_u32 s23, s27, 0
	global_load_lds_dwordx4 v[18:19], off
	s_mov_b32 m0, s24
	v_lshl_add_u64 v[18:19], s[22:23], 0, v[130:131]
	global_load_lds_dwordx4 v[18:19], off
	s_mov_b32 m0, s25
	v_lshl_add_u64 v[18:19], s[22:23], 0, v[132:133]
	global_load_lds_dwordx4 v[18:19], off
	s_mov_b32 m0, s44
	v_lshl_add_u64 v[18:19], v[250:251], 0, s[8:9]
	global_load_lds_dwordx4 v[18:19], off
	s_mov_b32 m0, s45
	v_lshl_add_u64 v[18:19], v[252:253], 0, s[8:9]
	global_load_lds_dwordx4 v[18:19], off
	s_setprio 1
	s_waitcnt vmcnt(8) lgkmcnt(0)
	s_barrier
	v_mfma_f32_16x16x32_bf16 v[18:21], v[62:65], v[58:61], v[146:149]
	v_mfma_f32_16x16x32_bf16 v[82:85], v[174:177], v[94:97], v[18:21]
	v_mfma_f32_16x16x32_bf16 v[18:21], v[198:201], v[58:61], v[150:153]
	v_mfma_f32_16x16x32_bf16 v[86:89], v[202:205], v[94:97], v[18:21]
	v_mfma_f32_16x16x32_bf16 v[18:21], v[62:65], v[178:181], v[154:157]
	v_mfma_f32_16x16x32_bf16 v[50:53], v[174:177], v[182:185], v[18:21]
	v_mfma_f32_16x16x32_bf16 v[18:21], v[198:201], v[178:181], v[158:161]
	v_mfma_f32_16x16x32_bf16 v[54:57], v[202:205], v[182:185], v[18:21]
	v_mfma_f32_16x16x32_bf16 v[18:21], v[62:65], v[210:213], v[162:165]
	v_mfma_f32_16x16x32_bf16 v[22:25], v[198:201], v[210:213], v[166:169]
	v_mfma_f32_16x16x32_bf16 v[2:5], v[62:65], v[230:233], v[2:5]
	v_mfma_f32_16x16x32_bf16 v[6:9], v[198:201], v[230:233], v[6:9]
	v_mfma_f32_16x16x32_bf16 v[18:21], v[174:177], v[226:229], v[18:21]
	v_mfma_f32_16x16x32_bf16 v[22:25], v[202:205], v[226:229], v[22:25]
	v_mfma_f32_16x16x32_bf16 v[2:5], v[174:177], v[234:237], v[2:5]
	v_mfma_f32_16x16x32_bf16 v[6:9], v[202:205], v[234:237], v[6:9]
	v_mfma_f32_16x16x32_bf16 v[10:13], v[206:209], v[58:61], v[10:13]
	v_mfma_f32_16x16x32_bf16 v[90:93], v[214:217], v[94:97], v[10:13]
	v_mfma_f32_16x16x32_bf16 v[10:13], v[218:221], v[58:61], v[14:17]
	v_mfma_f32_16x16x32_bf16 v[94:97], v[222:225], v[94:97], v[10:13]
	v_mfma_f32_16x16x32_bf16 v[10:13], v[206:209], v[178:181], v[26:29]
	v_mfma_f32_16x16x32_bf16 v[58:61], v[214:217], v[182:185], v[10:13]
	v_mfma_f32_16x16x32_bf16 v[10:13], v[218:221], v[178:181], v[30:33]
	v_mfma_f32_16x16x32_bf16 v[62:65], v[222:225], v[182:185], v[10:13]
	v_mfma_f32_16x16x32_bf16 v[10:13], v[206:209], v[210:213], v[186:189]
	v_mfma_f32_16x16x32_bf16 v[26:29], v[214:217], v[226:229], v[10:13]
	v_mfma_f32_16x16x32_bf16 v[10:13], v[218:221], v[210:213], v[190:193]
	v_mfma_f32_16x16x32_bf16 v[30:33], v[222:225], v[226:229], v[10:13]
	v_mfma_f32_16x16x32_bf16 v[10:13], v[206:209], v[230:233], v[194:197]
	v_mfma_f32_16x16x32_bf16 v[14:17], v[218:221], v[230:233], v[170:173]
	v_mfma_f32_16x16x32_bf16 v[10:13], v[214:217], v[234:237], v[10:13]
	v_mfma_f32_16x16x32_bf16 v[14:17], v[222:225], v[234:237], v[14:17]
	s_barrier
	s_setprio 0
	s_andn2_b64 vcc, exec, s[10:11]
	s_cbranch_vccnz .LBB0_208
	s_barrier

; #define PG8_STAGE(bufoff, gbase, voff) do { _Pragma("unroll") for (int _i = 0; _i < 2; ++_i) \
;         __builtin_amdgcn_global_load_lds((const unsigned*)((const char*)(gbase) + (voff)[_i]), (PG8_LAS unsigned*)(lds + (bufoff) + ldsw + _i * 8192), 16, 0, 0); } while (0)
; #define PG8_LDA(dst, b, h) do { _Pragma("unroll") for (int m = 0; m < 4; ++m) _Pragma("unroll") for (int k = 0; k < 2; ++k) dst[m][k] = *(const PG8_LAS bf16x8*)(lds + PG8_SA(b, h) + aoff + m * 2048 + k * 1024); } while (0)
; #define PG8_LDB(dst, b, h) do { _Pragma("unroll") for (int n = 0; n < 2; ++n) _Pragma("unroll") for (int k = 0; k < 2; ++k) dst[n][k] = *(const PG8_LAS bf16x8*)(lds + PG8_SB(b, h) + boff + n * 2048 + k * 1024); } while (0)
; #define PG8_MMA(ai, bj, At, Bt) do { __builtin_amdgcn_s_setprio(1); _Pragma("unroll") for (int m = 0; m < 4; ++m) _Pragma("unroll") for (int n = 0; n < 2; ++n) _Pragma("unroll") for (int k = 0; k < 2; ++k) \
;         acc[ai][bj][m][n] = __builtin_amdgcn_mfma_f32_16x16x32_bf16(Bt[n][k], At[m][k], acc[ai][bj][m][n], 0, 0, 0); __builtin_amdgcn_s_setprio(0); } while (0)
; #define PG8_WAIT_V(n) asm volatile("s_waitcnt vmcnt(" #n ")" ::: "memory")
; #define PG8_WAIT_L(n) asm volatile("s_waitcnt lgkmcnt(" #n ")" ::: "memory")
; #define PG8_BAR __builtin_amdgcn_s_barrier()
; #define PG8_SCHED __builtin_amdgcn_sched_barrier(0)
; template <class Epi, class Sched, bool ALIGN_EPI, int LMASK = -1, int LMASKB = LMASK>
; __device__ __forceinline__ void gemm_phase(PG8_LAS unsigned char* lds, const Gemm g, const Sched& S, const Epi& E) {
;     ...
;             const bool last = (t == nt - 2);
;             const char* a1 = cA + (size_t)(t + 1) * kstepA;
;             const char* a2 = last ? nA : cA + (size_t)(t + 2) * kstepA; const char* b2 = last ? nB : cB + (size_t)(t + 2) * kstepB;
;             const char* a3 = a2 + kstepA; const char* b3 = b2 + kstepB;
;             PG8_LDB(B0, 0, 0); PG8_LDB(B1, 0, 1); PG8_SCHED; PG8_LDA(At, 0, 0); PG8_STAGE(PG8_SA(1, 1), a1 + hstepA, voffA);
;             PG8_WAIT_V(8); PG8_WAIT_L(0); PG8_BAR; PG8_MMA(0, 0, At, B0); PG8_MMA(0, 1, At, B1); PG8_BAR; PG8_SCHED;
;             PG8_LDA(At, 0, 1); PG8_STAGE(PG8_SB(0, 0), b2, voffB); PG8_STAGE(PG8_SB(0, 1), b2 + hstepB, voffB); PG8_STAGE(PG8_SA(0, 0), a2, voffA);
.LBB0_284:
	s_add_u32 s10, s8, 0xfff00800
	s_addc_u32 s11, s9, -1
	s_add_i32 s55, 0, 0x10000
	s_cmp_eq_u32 s54, 60
	s_cselect_b32 s37, s0, s11
	s_cselect_b32 s36, s1, s10
	s_cselect_b32 s11, s2, s29
	s_cselect_b32 s10, s7, s27
	s_add_i32 s58, 0, 0x14000
	v_add_u32_e32 v142, s55, v161
	v_add_u32_e32 v154, s58, v161
	ds_read_b128 v[130:133], v142
	ds_read_b128 v[134:137], v142 offset:1024
	ds_read_b128 v[138:141], v142 offset:2048
	ds_read_b128 v[142:145], v142 offset:3072
	ds_read_b128 v[172:175], v154
	ds_read_b128 v[188:191], v154 offset:1024
	ds_read_b128 v[218:221], v154 offset:2048
	ds_read_b128 v[222:225], v154 offset:3072
	v_lshl_add_u64 v[154:155], s[8:9], 0, v[150:151]
	s_add_i32 m0, s45, 0xc000
	ds_read_b128 v[226:229], v171
	ds_read_b128 v[230:233], v171 offset:1024
	ds_read_b128 v[234:237], v171 offset:2048
	ds_read_b128 v[238:241], v171 offset:3072
	ds_read_b128 v[242:245], v171 offset:4096
	ds_read_b128 v[246:249], v171 offset:5120
	ds_read_b128 v[250:253], v171 offset:6144
	ds_read_b128 v[206:209], v171 offset:7168
	global_load_lds_dwordx4 v[154:155], off
	s_add_i32 m0, s45, 0xe000
	v_lshl_add_u64 v[154:155], s[8:9], 0, v[152:153]
	global_load_lds_dwordx4 v[154:155], off
	s_setprio 1
	s_waitcnt vmcnt(8) lgkmcnt(0)
	s_barrier
	v_mfma_f32_16x16x32_bf16 v[126:129], v[130:133], v[226:229], v[126:129]
	v_mfma_f32_16x16x32_bf16 v[122:125], v[138:141], v[226:229], v[122:125]
	v_mfma_f32_16x16x32_bf16 v[118:121], v[130:133], v[234:237], v[118:121]
	v_mfma_f32_16x16x32_bf16 v[110:113], v[138:141], v[234:237], v[110:113]
	v_mfma_f32_16x16x32_bf16 v[102:105], v[130:133], v[242:245], v[102:105]
	v_mfma_f32_16x16x32_bf16 v[94:97], v[138:141], v[242:245], v[94:97]
	v_mfma_f32_16x16x32_bf16 v[86:89], v[130:133], v[250:253], v[86:89]
	v_mfma_f32_16x16x32_bf16 v[78:81], v[138:141], v[250:253], v[78:81]
	v_mfma_f32_16x16x32_bf16 v[126:129], v[134:137], v[230:233], v[126:129]
	v_mfma_f32_16x16x32_bf16 v[122:125], v[142:145], v[230:233], v[122:125]
	v_mfma_f32_16x16x32_bf16 v[118:121], v[134:137], v[238:241], v[118:121]
	v_mfma_f32_16x16x32_bf16 v[110:113], v[142:145], v[238:241], v[110:113]
	v_mfma_f32_16x16x32_bf16 v[102:105], v[134:137], v[246:249], v[102:105]
	v_mfma_f32_16x16x32_bf16 v[94:97], v[142:145], v[246:249], v[94:97]
	v_mfma_f32_16x16x32_bf16 v[86:89], v[134:137], v[206:209], v[86:89]
	v_mfma_f32_16x16x32_bf16 v[78:81], v[142:145], v[206:209], v[78:81]
	v_mfma_f32_16x16x32_bf16 v[114:117], v[172:175], v[226:229], v[114:117]
	v_mfma_f32_16x16x32_bf16 v[106:109], v[218:221], v[226:229], v[106:109]
	v_mfma_f32_16x16x32_bf16 v[98:101], v[172:175], v[234:237], v[98:101]
	v_mfma_f32_16x16x32_bf16 v[90:93], v[218:221], v[234:237], v[90:93]
	v_mfma_f32_16x16x32_bf16 v[82:85], v[172:175], v[242:245], v[82:85]
	v_mfma_f32_16x16x32_bf16 v[74:77], v[218:221], v[242:245], v[74:77]
	v_mfma_f32_16x16x32_bf16 v[70:73], v[172:175], v[250:253], v[70:73]
	v_mfma_f32_16x16x32_bf16 v[66:69], v[218:221], v[250:253], v[66:69]
	v_mfma_f32_16x16x32_bf16 v[114:117], v[188:191], v[230:233], v[114:117]
	v_mfma_f32_16x16x32_bf16 v[106:109], v[222:225], v[230:233], v[106:109]
	v_mfma_f32_16x16x32_bf16 v[98:101], v[188:191], v[238:241], v[98:101]
	v_mfma_f32_16x16x32_bf16 v[90:93], v[222:225], v[238:241], v[90:93]
	v_mfma_f32_16x16x32_bf16 v[82:85], v[188:191], v[246:249], v[82:85]
	v_mfma_f32_16x16x32_bf16 v[74:77], v[222:225], v[246:249], v[74:77]
	v_mfma_f32_16x16x32_bf16 v[70:73], v[188:191], v[206:209], v[70:73]
	v_mfma_f32_16x16x32_bf16 v[66:69], v[222:225], v[206:209], v[66:69]
	s_barrier
	s_setprio 0
	s_add_i32 s55, s55, s43
	v_lshl_add_u64 v[154:155], s[10:11], 0, v[148:149]
	s_mov_b32 m0, s55
	ds_read_b128 v[206:209], v171 offset:16384
	ds_read_b128 v[226:229], v171 offset:17408
	ds_read_b128 v[230:233], v171 offset:18432
	ds_read_b128 v[234:237], v171 offset:19456
	ds_read_b128 v[238:241], v171 offset:20480
	ds_read_b128 v[242:245], v171 offset:21504
	ds_read_b128 v[246:249], v171 offset:22528
	ds_read_b128 v[250:253], v171 offset:23552
	global_load_lds_dwordx4 v[154:155], off
	s_add_i32 m0, s55, 0x2000
	s_add_u32 s56, s10, 0x100000
	v_lshl_add_u64 v[176:177], s[10:11], 0, v[146:147]
	s_addc_u32 s57, s11, 0
	s_add_i32 s55, s58, s43
	global_load_lds_dwordx4 v[176:177], off
	v_lshl_add_u64 v[194:195], s[56:57], 0, v[148:149]
	s_mov_b32 m0, s55
	v_lshl_add_u64 v[210:211], s[36:37], 0, v[146:147]
	global_load_lds_dwordx4 v[194:195], off
	s_add_i32 m0, s55, 0x2000
	v_lshl_add_u64 v[194:195], s[56:57], 0, v[146:147]
	global_load_lds_dwordx4 v[194:195], off
	s_mov_b32 m0, s45
	v_lshl_add_u64 v[194:195], s[36:37], 0, v[148:149]
	global_load_lds_dwordx4 v[194:195], off
	s_mov_b32 m0, s46
	s_nop 0
	global_load_lds_dwordx4 v[210:211], off
	s_setprio 1
	s_waitcnt vmcnt(8) lgkmcnt(0)
	s_barrier
; #define PG8_STAGE(bufoff, gbase, voff) do { _Pragma("unroll") for (int _i = 0; _i < 2; ++_i) \
;         __builtin_amdgcn_global_load_lds((const unsigned*)((const char*)(gbase) + (voff)[_i]), (PG8_LAS unsigned*)(lds + (bufoff) + ldsw + _i * 8192), 16, 0, 0); } while (0)
; #define PG8_LDA(dst, b, h) do { _Pragma("unroll") for (int m = 0; m < 4; ++m) _Pragma("unroll") for (int k = 0; k < 2; ++k) dst[m][k] = *(const PG8_LAS bf16x8*)(lds + PG8_SA(b, h) + aoff + m * 2048 + k * 1024); } while (0)
; #define PG8_LDB(dst, b, h) do { _Pragma("unroll") for (int n = 0; n < 2; ++n) _Pragma("unroll") for (int k = 0; k < 2; ++k) dst[n][k] = *(const PG8_LAS bf16x8*)(lds + PG8_SB(b, h) + boff + n * 2048 + k * 1024); } while (0)
; #define PG8_MMA(ai, bj, At, Bt) do { __builtin_amdgcn_s_setprio(1); _Pragma("unroll") for (int m = 0; m < 4; ++m) _Pragma("unroll") for (int n = 0; n < 2; ++n) _Pragma("unroll") for (int k = 0; k < 2; ++k) \
;         acc[ai][bj][m][n] = __builtin_amdgcn_mfma_f32_16x16x32_bf16(Bt[n][k], At[m][k], acc[ai][bj][m][n], 0, 0, 0); __builtin_amdgcn_s_setprio(0); } while (0)
; #define PG8_WAIT_V(n) asm volatile("s_waitcnt vmcnt(" #n ")" ::: "memory")
; #define PG8_WAIT_L(n) asm volatile("s_waitcnt lgkmcnt(" #n ")" ::: "memory")
; #define PG8_BAR __builtin_amdgcn_s_barrier()
; #define PG8_SCHED __builtin_amdgcn_sched_barrier(0)
; template <class Epi, class Sched, bool ALIGN_EPI, int LMASK = -1, int LMASKB = LMASK>
; __device__ __forceinline__ void gemm_phase(PG8_LAS unsigned char* lds, const Gemm g, const Sched& S, const Epi& E) {
;     ...
;             PG8_WAIT_V(8); PG8_WAIT_L(0); PG8_BAR; PG8_MMA(1, 0, At, B0); PG8_MMA(1, 1, At, B1); PG8_BAR; PG8_SCHED;
;             PG8_LDB(B0, 1, 0); PG8_LDB(B1, 1, 1); PG8_SCHED; PG8_LDA(At, 1, 0); PG8_STAGE(PG8_SA(0, 1), a2 + hstepA, voffA);
;             PG8_WAIT_V(8); PG8_WAIT_L(0); PG8_BAR; PG8_MMA(0, 0, At, B0); PG8_MMA(0, 1, At, B1); PG8_BAR; PG8_SCHED;
	v_mfma_f32_16x16x32_bf16 v[62:65], v[130:133], v[206:209], v[62:65]
	v_mfma_f32_16x16x32_bf16 v[58:61], v[138:141], v[206:209], v[58:61]
	v_mfma_f32_16x16x32_bf16 v[54:57], v[130:133], v[230:233], v[54:57]
	v_mfma_f32_16x16x32_bf16 v[46:49], v[138:141], v[230:233], v[46:49]
	v_mfma_f32_16x16x32_bf16 v[38:41], v[130:133], v[238:241], v[38:41]
	v_mfma_f32_16x16x32_bf16 v[30:33], v[138:141], v[238:241], v[30:33]
	v_mfma_f32_16x16x32_bf16 v[22:25], v[130:133], v[246:249], v[22:25]
	v_mfma_f32_16x16x32_bf16 v[14:17], v[138:141], v[246:249], v[14:17]
	v_mfma_f32_16x16x32_bf16 v[62:65], v[134:137], v[226:229], v[62:65]
	v_mfma_f32_16x16x32_bf16 v[58:61], v[142:145], v[226:229], v[58:61]
	v_mfma_f32_16x16x32_bf16 v[54:57], v[134:137], v[234:237], v[54:57]
	v_mfma_f32_16x16x32_bf16 v[46:49], v[142:145], v[234:237], v[46:49]
	v_mfma_f32_16x16x32_bf16 v[38:41], v[134:137], v[242:245], v[38:41]
	v_mfma_f32_16x16x32_bf16 v[30:33], v[142:145], v[242:245], v[30:33]
	v_mfma_f32_16x16x32_bf16 v[22:25], v[134:137], v[250:253], v[22:25]
	v_mfma_f32_16x16x32_bf16 v[14:17], v[142:145], v[250:253], v[14:17]
	v_mfma_f32_16x16x32_bf16 v[50:53], v[172:175], v[206:209], v[50:53]
	v_mfma_f32_16x16x32_bf16 v[42:45], v[218:221], v[206:209], v[42:45]
	v_mfma_f32_16x16x32_bf16 v[34:37], v[172:175], v[230:233], v[34:37]
	v_mfma_f32_16x16x32_bf16 v[26:29], v[218:221], v[230:233], v[26:29]
	v_mfma_f32_16x16x32_bf16 v[18:21], v[172:175], v[238:241], v[18:21]
	v_mfma_f32_16x16x32_bf16 v[10:13], v[218:221], v[238:241], v[10:13]
	v_mfma_f32_16x16x32_bf16 v[6:9], v[172:175], v[246:249], v[6:9]
	v_mfma_f32_16x16x32_bf16 v[2:5], v[218:221], v[246:249], v[2:5]
	v_mfma_f32_16x16x32_bf16 v[50:53], v[188:191], v[226:229], v[50:53]
	v_mfma_f32_16x16x32_bf16 v[42:45], v[222:225], v[226:229], v[42:45]
	v_mfma_f32_16x16x32_bf16 v[34:37], v[188:191], v[234:237], v[34:37]
	v_mfma_f32_16x16x32_bf16 v[26:29], v[222:225], v[234:237], v[26:29]
	v_mfma_f32_16x16x32_bf16 v[18:21], v[188:191], v[242:245], v[18:21]
	v_mfma_f32_16x16x32_bf16 v[10:13], v[222:225], v[242:245], v[10:13]
	v_mfma_f32_16x16x32_bf16 v[6:9], v[188:191], v[250:253], v[6:9]
	v_mfma_f32_16x16x32_bf16 v[2:5], v[222:225], v[250:253], v[2:5]
	s_barrier
	s_setprio 0
	s_add_i32 s55, 0, 0x18000
	s_add_i32 s56, 0, 0x1c000
	v_add_u32_e32 v142, s55, v161
	v_add_u32_e32 v156, s56, v161
	ds_read_b128 v[130:133], v142
	ds_read_b128 v[134:137], v142 offset:1024
	ds_read_b128 v[138:141], v142 offset:2048
	ds_read_b128 v[142:145], v142 offset:3072
	ds_read_b128 v[172:175], v156
	ds_read_b128 v[188:191], v156 offset:1024
	ds_read_b128 v[206:209], v156 offset:2048
	ds_read_b128 v[218:221], v156 offset:3072
	s_add_u32 s36, s36, 0x100000
	s_addc_u32 s37, s37, 0
	s_mov_b32 m0, s47
	v_lshl_add_u64 v[212:213], s[36:37], 0, v[148:149]
	ds_read_b128 v[222:225], v171 offset:32768
	ds_read_b128 v[226:229], v171 offset:33792
	ds_read_b128 v[230:233], v171 offset:34816
	ds_read_b128 v[234:237], v171 offset:35840
	ds_read_b128 v[238:241], v171 offset:36864
	ds_read_b128 v[242:245], v171 offset:37888
	ds_read_b128 v[246:249], v171 offset:38912
	ds_read_b128 v[250:253], v171 offset:39936
	global_load_lds_dwordx4 v[212:213], off
	s_mov_b32 m0, s48
	v_lshl_add_u64 v[212:213], s[36:37], 0, v[146:147]
	global_load_lds_dwordx4 v[212:213], off
	s_setprio 1
	s_waitcnt vmcnt(8) lgkmcnt(0)
	s_barrier
	v_mfma_f32_16x16x32_bf16 v[126:129], v[130:133], v[222:225], v[126:129]
	v_mfma_f32_16x16x32_bf16 v[122:125], v[138:141], v[222:225], v[122:125]
	v_mfma_f32_16x16x32_bf16 v[118:121], v[130:133], v[230:233], v[118:121]
	v_mfma_f32_16x16x32_bf16 v[110:113], v[138:141], v[230:233], v[110:113]
	v_mfma_f32_16x16x32_bf16 v[102:105], v[130:133], v[238:241], v[102:105]
	v_mfma_f32_16x16x32_bf16 v[94:97], v[138:141], v[238:241], v[94:97]
	v_mfma_f32_16x16x32_bf16 v[86:89], v[130:133], v[246:249], v[86:89]
	v_mfma_f32_16x16x32_bf16 v[78:81], v[138:141], v[246:249], v[78:81]
	v_mfma_f32_16x16x32_bf16 v[126:129], v[134:137], v[226:229], v[126:129]
	v_mfma_f32_16x16x32_bf16 v[122:125], v[142:145], v[226:229], v[122:125]
	v_mfma_f32_16x16x32_bf16 v[118:121], v[134:137], v[234:237], v[118:121]
	v_mfma_f32_16x16x32_bf16 v[110:113], v[142:145], v[234:237], v[110:113]
	v_mfma_f32_16x16x32_bf16 v[102:105], v[134:137], v[242:245], v[102:105]
	v_mfma_f32_16x16x32_bf16 v[94:97], v[142:145], v[242:245], v[94:97]
	v_mfma_f32_16x16x32_bf16 v[86:89], v[134:137], v[250:253], v[86:89]
	v_mfma_f32_16x16x32_bf16 v[78:81], v[142:145], v[250:253], v[78:81]
	v_mfma_f32_16x16x32_bf16 v[114:117], v[172:175], v[222:225], v[114:117]
	v_mfma_f32_16x16x32_bf16 v[106:109], v[206:209], v[222:225], v[106:109]
	v_mfma_f32_16x16x32_bf16 v[98:101], v[172:175], v[230:233], v[98:101]
	v_mfma_f32_16x16x32_bf16 v[90:93], v[206:209], v[230:233], v[90:93]
	v_mfma_f32_16x16x32_bf16 v[82:85], v[172:175], v[238:241], v[82:85]
	v_mfma_f32_16x16x32_bf16 v[74:77], v[206:209], v[238:241], v[74:77]
	v_mfma_f32_16x16x32_bf16 v[70:73], v[172:175], v[246:249], v[70:73]
	v_mfma_f32_16x16x32_bf16 v[66:69], v[206:209], v[246:249], v[66:69]
	v_mfma_f32_16x16x32_bf16 v[114:117], v[188:191], v[226:229], v[114:117]
	v_mfma_f32_16x16x32_bf16 v[106:109], v[218:221], v[226:229], v[106:109]
	v_mfma_f32_16x16x32_bf16 v[98:101], v[188:191], v[234:237], v[98:101]
	v_mfma_f32_16x16x32_bf16 v[90:93], v[218:221], v[234:237], v[90:93]
	v_mfma_f32_16x16x32_bf16 v[82:85], v[188:191], v[242:245], v[82:85]
	v_mfma_f32_16x16x32_bf16 v[74:77], v[218:221], v[242:245], v[74:77]
	v_mfma_f32_16x16x32_bf16 v[70:73], v[188:191], v[250:253], v[70:73]
	v_mfma_f32_16x16x32_bf16 v[66:69], v[218:221], v[250:253], v[66:69]
	s_barrier
; #define PG8_STAGE(bufoff, gbase, voff) do { _Pragma("unroll") for (int _i = 0; _i < 2; ++_i) \
;         __builtin_amdgcn_global_load_lds((const unsigned*)((const char*)(gbase) + (voff)[_i]), (PG8_LAS unsigned*)(lds + (bufoff) + ldsw + _i * 8192), 16, 0, 0); } while (0)
; #define PG8_LDA(dst, b, h) do { _Pragma("unroll") for (int m = 0; m < 4; ++m) _Pragma("unroll") for (int k = 0; k < 2; ++k) dst[m][k] = *(const PG8_LAS bf16x8*)(lds + PG8_SA(b, h) + aoff + m * 2048 + k * 1024); } while (0)
; #define PG8_MMA(ai, bj, At, Bt) do { __builtin_amdgcn_s_setprio(1); _Pragma("unroll") for (int m = 0; m < 4; ++m) _Pragma("unroll") for (int n = 0; n < 2; ++n) _Pragma("unroll") for (int k = 0; k < 2; ++k) \
;         acc[ai][bj][m][n] = __builtin_amdgcn_mfma_f32_16x16x32_bf16(Bt[n][k], At[m][k], acc[ai][bj][m][n], 0, 0, 0); __builtin_amdgcn_s_setprio(0); } while (0)
; #define PG8_WAIT_V(n) asm volatile("s_waitcnt vmcnt(" #n ")" ::: "memory")
; #define PG8_WAIT_L(n) asm volatile("s_waitcnt lgkmcnt(" #n ")" ::: "memory")
; #define PG8_BAR __builtin_amdgcn_s_barrier()
; #define PG8_SCHED __builtin_amdgcn_sched_barrier(0)
; template <class Epi, class Sched, bool ALIGN_EPI, int LMASK = -1, int LMASKB = LMASK>
; __device__ __forceinline__ void gemm_phase(PG8_LAS unsigned char* lds, const Gemm g, const Sched& S, const Epi& E) {
;     ...
;             PG8_LDA(At, 1, 1); PG8_STAGE(PG8_SB(1, 0), b3, voffB); PG8_STAGE(PG8_SB(1, 1), b3 + hstepB, voffB); PG8_STAGE(PG8_SA(1, 0), a3, voffA);
;             PG8_WAIT_V(8); PG8_WAIT_L(0); PG8_BAR; PG8_MMA(1, 0, At, B0); PG8_MMA(1, 1, At, B1); PG8_BAR; PG8_SCHED;
;         }
;         if constexpr (ALIGN_EPI) { if (wr == 0) PG8_BAR; }
	s_setprio 0
	s_add_i32 s36, s55, s43
	v_lshl_add_u64 v[154:155], v[154:155], 0, s[80:81]
	s_mov_b32 m0, s36
	ds_read_b128 v[222:225], v171 offset:49152
	ds_read_b128 v[226:229], v171 offset:50176
	ds_read_b128 v[230:233], v171 offset:51200
	ds_read_b128 v[234:237], v171 offset:52224
	ds_read_b128 v[238:241], v171 offset:53248
	ds_read_b128 v[242:245], v171 offset:54272
	ds_read_b128 v[246:249], v171 offset:55296
	ds_read_b128 v[250:253], v171 offset:56320
	global_load_lds_dwordx4 v[154:155], off
	s_add_i32 m0, s36, 0x2000
	s_add_u32 s10, s10, 0x100800
	v_lshl_add_u64 v[154:155], v[176:177], 0, s[80:81]
	s_addc_u32 s11, s11, 0
	s_add_i32 s36, s56, s43
	global_load_lds_dwordx4 v[154:155], off
	s_mov_b32 m0, s36
	v_lshl_add_u64 v[154:155], s[10:11], 0, v[148:149]
	global_load_lds_dwordx4 v[154:155], off
	s_add_i32 m0, s36, 0x2000
	v_lshl_add_u64 v[154:155], s[10:11], 0, v[146:147]
	global_load_lds_dwordx4 v[154:155], off
	s_mov_b32 m0, s49
	v_lshl_add_u64 v[154:155], v[194:195], 0, s[80:81]
	global_load_lds_dwordx4 v[154:155], off
	s_mov_b32 m0, s50
	v_lshl_add_u64 v[154:155], v[210:211], 0, s[80:81]
	global_load_lds_dwordx4 v[154:155], off
	s_setprio 1
	s_waitcnt vmcnt(8) lgkmcnt(0)
	s_barrier
	v_mfma_f32_16x16x32_bf16 v[62:65], v[130:133], v[222:225], v[62:65]
	v_mfma_f32_16x16x32_bf16 v[58:61], v[138:141], v[222:225], v[58:61]
	v_mfma_f32_16x16x32_bf16 v[54:57], v[130:133], v[230:233], v[54:57]
	v_mfma_f32_16x16x32_bf16 v[46:49], v[138:141], v[230:233], v[46:49]
	v_mfma_f32_16x16x32_bf16 v[38:41], v[130:133], v[238:241], v[38:41]
	v_mfma_f32_16x16x32_bf16 v[30:33], v[138:141], v[238:241], v[30:33]
	v_mfma_f32_16x16x32_bf16 v[22:25], v[130:133], v[246:249], v[22:25]
	v_mfma_f32_16x16x32_bf16 v[14:17], v[138:141], v[246:249], v[14:17]
	v_mfma_f32_16x16x32_bf16 v[62:65], v[134:137], v[226:229], v[62:65]
	v_mfma_f32_16x16x32_bf16 v[58:61], v[142:145], v[226:229], v[58:61]
	v_mfma_f32_16x16x32_bf16 v[54:57], v[134:137], v[234:237], v[54:57]
	v_mfma_f32_16x16x32_bf16 v[46:49], v[142:145], v[234:237], v[46:49]
	v_mfma_f32_16x16x32_bf16 v[38:41], v[134:137], v[242:245], v[38:41]
	v_mfma_f32_16x16x32_bf16 v[30:33], v[142:145], v[242:245], v[30:33]
	v_mfma_f32_16x16x32_bf16 v[22:25], v[134:137], v[250:253], v[22:25]
	v_mfma_f32_16x16x32_bf16 v[14:17], v[142:145], v[250:253], v[14:17]
	v_mfma_f32_16x16x32_bf16 v[50:53], v[172:175], v[222:225], v[50:53]
	v_mfma_f32_16x16x32_bf16 v[42:45], v[206:209], v[222:225], v[42:45]
	v_mfma_f32_16x16x32_bf16 v[34:37], v[172:175], v[230:233], v[34:37]
	v_mfma_f32_16x16x32_bf16 v[26:29], v[206:209], v[230:233], v[26:29]
	v_mfma_f32_16x16x32_bf16 v[18:21], v[172:175], v[238:241], v[18:21]
	v_mfma_f32_16x16x32_bf16 v[10:13], v[206:209], v[238:241], v[10:13]
	v_mfma_f32_16x16x32_bf16 v[6:9], v[172:175], v[246:249], v[6:9]
	v_mfma_f32_16x16x32_bf16 v[2:5], v[206:209], v[246:249], v[2:5]
	v_mfma_f32_16x16x32_bf16 v[50:53], v[188:191], v[226:229], v[50:53]
	v_mfma_f32_16x16x32_bf16 v[42:45], v[218:221], v[226:229], v[42:45]
	v_mfma_f32_16x16x32_bf16 v[34:37], v[188:191], v[234:237], v[34:37]
	v_mfma_f32_16x16x32_bf16 v[26:29], v[218:221], v[234:237], v[26:29]
	v_mfma_f32_16x16x32_bf16 v[18:21], v[188:191], v[242:245], v[18:21]
	v_mfma_f32_16x16x32_bf16 v[10:13], v[218:221], v[242:245], v[10:13]
	v_mfma_f32_16x16x32_bf16 v[6:9], v[188:191], v[250:253], v[6:9]
	v_mfma_f32_16x16x32_bf16 v[2:5], v[218:221], v[250:253], v[2:5]
	s_barrier
	s_setprio 0
	s_add_i32 s54, s54, 2
	s_add_u32 s8, s8, 0x1000
	s_addc_u32 s9, s9, 0
	s_add_u32 s27, s27, 0x1000
	s_addc_u32 s29, s29, 0
	s_cmp_gt_u32 s54, 61
	s_cbranch_scc0 .LBB0_284
	s_and_b64 vcc, exec, s[22:23]
	s_cbranch_vccz .LBB0_287
	s_barrier

; #define PG8_STAGE(bufoff, gbase, voff) do { _Pragma("unroll") for (int _i = 0; _i < 2; ++_i) \
;         __builtin_amdgcn_global_load_lds((const unsigned*)((const char*)(gbase) + (voff)[_i]), (PG8_LAS unsigned*)(lds + (bufoff) + ldsw + _i * 8192), 16, 0, 0); } while (0)
; #define PG8_LDA(dst, b, h) do { _Pragma("unroll") for (int m = 0; m < 4; ++m) _Pragma("unroll") for (int k = 0; k < 2; ++k) dst[m][k] = *(const PG8_LAS bf16x8*)(lds + PG8_SA(b, h) + aoff + m * 2048 + k * 1024); } while (0)
; #define PG8_LDB(dst, b, h) do { _Pragma("unroll") for (int n = 0; n < 2; ++n) _Pragma("unroll") for (int k = 0; k < 2; ++k) dst[n][k] = *(const PG8_LAS bf16x8*)(lds + PG8_SB(b, h) + boff + n * 2048 + k * 1024); } while (0)
; #define PG8_MMA(ai, bj, At, Bt) do { __builtin_amdgcn_s_setprio(1); _Pragma("unroll") for (int m = 0; m < 4; ++m) _Pragma("unroll") for (int n = 0; n < 2; ++n) _Pragma("unroll") for (int k = 0; k < 2; ++k) \
;         acc[ai][bj][m][n] = __builtin_amdgcn_mfma_f32_16x16x32_bf16(Bt[n][k], At[m][k], acc[ai][bj][m][n], 0, 0, 0); __builtin_amdgcn_s_setprio(0); } while (0)
; #define PG8_WAIT_V(n) asm volatile("s_waitcnt vmcnt(" #n ")" ::: "memory")
; #define PG8_WAIT_L(n) asm volatile("s_waitcnt lgkmcnt(" #n ")" ::: "memory")
; #define PG8_BAR __builtin_amdgcn_s_barrier()
; #define PG8_SCHED __builtin_amdgcn_sched_barrier(0)
; template <class Epi, class Sched, bool ALIGN_EPI, int LMASK = -1, int LMASKB = LMASK>
; __device__ __forceinline__ void gemm_phase(PG8_LAS unsigned char* lds, const Gemm g, const Sched& S, const Epi& E) {
;     ...
;             const bool last = (t == nt - 2);
;             const char* a1 = cA + (size_t)(t + 1) * kstepA;
;             const char* a2 = last ? nA : cA + (size_t)(t + 2) * kstepA; const char* b2 = last ? nB : cB + (size_t)(t + 2) * kstepB;
;             const char* a3 = a2 + kstepA; const char* b3 = b2 + kstepB;
;             PG8_LDB(B0, 0, 0); PG8_LDB(B1, 0, 1); PG8_SCHED; PG8_LDA(At, 0, 0); PG8_STAGE(PG8_SA(1, 1), a1 + hstepA, voffA);
;             PG8_WAIT_V(8); PG8_WAIT_L(0); PG8_BAR; PG8_MMA(0, 0, At, B0); PG8_MMA(0, 1, At, B1); PG8_BAR; PG8_SCHED;
;             PG8_LDA(At, 0, 1); PG8_STAGE(PG8_SB(0, 0), b2, voffB); PG8_STAGE(PG8_SB(0, 1), b2 + hstepB, voffB); PG8_STAGE(PG8_SA(0, 0), a2, voffA);
.LBB0_580:
	s_add_u32 s30, s28, 0xfff00800
	s_addc_u32 s31, s29, -1
	s_add_i32 s51, 0, 0x10000
	s_cmp_eq_u32 s50, 60
	s_cselect_b32 s35, s19, s31
	s_cselect_b32 s34, s25, s30
	v_add_u32_e32 v146, s51, v149
	s_cselect_b32 s31, s17, s49
	s_cselect_b32 s30, s47, s48
	s_add_i32 s54, 0, 0x14000
	ds_read_b128 v[130:133], v146
	ds_read_b128 v[142:145], v146 offset:1024
	ds_read_b128 v[152:155], v146 offset:2048
	ds_read_b128 v[156:159], v146 offset:3072
	v_add_u32_e32 v146, s54, v149
	ds_read_b128 v[160:163], v146
	ds_read_b128 v[164:167], v146 offset:1024
	ds_read_b128 v[168:171], v146 offset:2048
	ds_read_b128 v[172:175], v146 offset:3072
	v_lshl_add_u64 v[146:147], s[28:29], 0, v[138:139]
	s_add_i32 m0, s27, 0xc000
	ds_read_b128 v[188:191], v151
	ds_read_b128 v[206:209], v151 offset:1024
	ds_read_b128 v[218:221], v151 offset:2048
	ds_read_b128 v[222:225], v151 offset:3072
	ds_read_b128 v[226:229], v151 offset:4096
	ds_read_b128 v[230:233], v151 offset:5120
	ds_read_b128 v[234:237], v151 offset:6144
	ds_read_b128 v[238:241], v151 offset:7168
	global_load_lds_dwordx4 v[146:147], off
	s_add_i32 m0, s27, 0xe000
	v_lshl_add_u64 v[146:147], s[28:29], 0, v[140:141]
	global_load_lds_dwordx4 v[146:147], off
	s_setprio 1
	s_waitcnt vmcnt(8) lgkmcnt(0)
	s_barrier
	v_mfma_f32_16x16x32_bf16 v[126:129], v[130:133], v[188:191], v[126:129]
	v_mfma_f32_16x16x32_bf16 v[122:125], v[152:155], v[188:191], v[122:125]
	v_mfma_f32_16x16x32_bf16 v[110:113], v[130:133], v[218:221], v[110:113]
	v_mfma_f32_16x16x32_bf16 v[106:109], v[152:155], v[218:221], v[106:109]
	v_mfma_f32_16x16x32_bf16 v[94:97], v[130:133], v[226:229], v[94:97]
	v_mfma_f32_16x16x32_bf16 v[90:93], v[152:155], v[226:229], v[90:93]
	v_mfma_f32_16x16x32_bf16 v[78:81], v[130:133], v[234:237], v[78:81]
	v_mfma_f32_16x16x32_bf16 v[74:77], v[152:155], v[234:237], v[74:77]
	v_mfma_f32_16x16x32_bf16 v[126:129], v[142:145], v[206:209], v[126:129]
	v_mfma_f32_16x16x32_bf16 v[122:125], v[156:159], v[206:209], v[122:125]
	v_mfma_f32_16x16x32_bf16 v[110:113], v[142:145], v[222:225], v[110:113]
	v_mfma_f32_16x16x32_bf16 v[106:109], v[156:159], v[222:225], v[106:109]
	v_mfma_f32_16x16x32_bf16 v[94:97], v[142:145], v[230:233], v[94:97]
	v_mfma_f32_16x16x32_bf16 v[90:93], v[156:159], v[230:233], v[90:93]
	v_mfma_f32_16x16x32_bf16 v[78:81], v[142:145], v[238:241], v[78:81]
	v_mfma_f32_16x16x32_bf16 v[74:77], v[156:159], v[238:241], v[74:77]
	v_mfma_f32_16x16x32_bf16 v[118:121], v[160:163], v[188:191], v[118:121]
	v_mfma_f32_16x16x32_bf16 v[114:117], v[168:171], v[188:191], v[114:117]
	v_mfma_f32_16x16x32_bf16 v[102:105], v[160:163], v[218:221], v[102:105]
	v_mfma_f32_16x16x32_bf16 v[98:101], v[168:171], v[218:221], v[98:101]
	v_mfma_f32_16x16x32_bf16 v[86:89], v[160:163], v[226:229], v[86:89]
	v_mfma_f32_16x16x32_bf16 v[82:85], v[168:171], v[226:229], v[82:85]
	v_mfma_f32_16x16x32_bf16 v[70:73], v[160:163], v[234:237], v[70:73]
	v_mfma_f32_16x16x32_bf16 v[66:69], v[168:171], v[234:237], v[66:69]
	v_mfma_f32_16x16x32_bf16 v[118:121], v[164:167], v[206:209], v[118:121]
	v_mfma_f32_16x16x32_bf16 v[114:117], v[172:175], v[206:209], v[114:117]
	v_mfma_f32_16x16x32_bf16 v[102:105], v[164:167], v[222:225], v[102:105]
	v_mfma_f32_16x16x32_bf16 v[98:101], v[172:175], v[222:225], v[98:101]
	v_mfma_f32_16x16x32_bf16 v[86:89], v[164:167], v[230:233], v[86:89]
	v_mfma_f32_16x16x32_bf16 v[82:85], v[172:175], v[230:233], v[82:85]
	v_mfma_f32_16x16x32_bf16 v[70:73], v[164:167], v[238:241], v[70:73]
	v_mfma_f32_16x16x32_bf16 v[66:69], v[172:175], v[238:241], v[66:69]
	s_barrier
	s_setprio 0
	s_add_i32 s51, s51, s38
	v_lshl_add_u64 v[146:147], s[30:31], 0, v[134:135]
	s_mov_b32 m0, s51
	ds_read_b128 v[188:191], v151 offset:16384
	ds_read_b128 v[206:209], v151 offset:17408
	ds_read_b128 v[218:221], v151 offset:18432
	ds_read_b128 v[222:225], v151 offset:19456
	ds_read_b128 v[226:229], v151 offset:20480
	ds_read_b128 v[230:233], v151 offset:21504
	ds_read_b128 v[234:237], v151 offset:22528
	ds_read_b128 v[238:241], v151 offset:23552
	global_load_lds_dwordx4 v[146:147], off
	s_add_i32 m0, s51, 0x2000
	s_add_u32 s52, s30, 0x100000
	v_lshl_add_u64 v[176:177], s[30:31], 0, v[136:137]
	s_addc_u32 s53, s31, 0
	s_add_i32 s51, s54, s38
	global_load_lds_dwordx4 v[176:177], off
	v_lshl_add_u64 v[194:195], s[52:53], 0, v[134:135]
	s_mov_b32 m0, s51
	v_lshl_add_u64 v[210:211], s[34:35], 0, v[136:137]
	global_load_lds_dwordx4 v[194:195], off
	s_add_i32 m0, s51, 0x2000
	v_lshl_add_u64 v[194:195], s[52:53], 0, v[136:137]
	global_load_lds_dwordx4 v[194:195], off
	s_mov_b32 m0, s27
	v_lshl_add_u64 v[194:195], s[34:35], 0, v[134:135]
	global_load_lds_dwordx4 v[194:195], off
	s_mov_b32 m0, s39
	s_nop 0
	global_load_lds_dwordx4 v[210:211], off
	s_setprio 1
	s_waitcnt vmcnt(8) lgkmcnt(0)
	s_barrier
; #define PG8_STAGE(bufoff, gbase, voff) do { _Pragma("unroll") for (int _i = 0; _i < 2; ++_i) \
;         __builtin_amdgcn_global_load_lds((const unsigned*)((const char*)(gbase) + (voff)[_i]), (PG8_LAS unsigned*)(lds + (bufoff) + ldsw + _i * 8192), 16, 0, 0); } while (0)
; #define PG8_LDA(dst, b, h) do { _Pragma("unroll") for (int m = 0; m < 4; ++m) _Pragma("unroll") for (int k = 0; k < 2; ++k) dst[m][k] = *(const PG8_LAS bf16x8*)(lds + PG8_SA(b, h) + aoff + m * 2048 + k * 1024); } while (0)
; #define PG8_LDB(dst, b, h) do { _Pragma("unroll") for (int n = 0; n < 2; ++n) _Pragma("unroll") for (int k = 0; k < 2; ++k) dst[n][k] = *(const PG8_LAS bf16x8*)(lds + PG8_SB(b, h) + boff + n * 2048 + k * 1024); } while (0)
; #define PG8_MMA(ai, bj, At, Bt) do { __builtin_amdgcn_s_setprio(1); _Pragma("unroll") for (int m = 0; m < 4; ++m) _Pragma("unroll") for (int n = 0; n < 2; ++n) _Pragma("unroll") for (int k = 0; k < 2; ++k) \
;         acc[ai][bj][m][n] = __builtin_amdgcn_mfma_f32_16x16x32_bf16(Bt[n][k], At[m][k], acc[ai][bj][m][n], 0, 0, 0); __builtin_amdgcn_s_setprio(0); } while (0)
; #define PG8_WAIT_V(n) asm volatile("s_waitcnt vmcnt(" #n ")" ::: "memory")
; #define PG8_WAIT_L(n) asm volatile("s_waitcnt lgkmcnt(" #n ")" ::: "memory")
; #define PG8_BAR __builtin_amdgcn_s_barrier()
; #define PG8_SCHED __builtin_amdgcn_sched_barrier(0)
; template <class Epi, class Sched, bool ALIGN_EPI, int LMASK = -1, int LMASKB = LMASK>
; __device__ __forceinline__ void gemm_phase(PG8_LAS unsigned char* lds, const Gemm g, const Sched& S, const Epi& E) {
;     ...
;             PG8_WAIT_V(8); PG8_WAIT_L(0); PG8_BAR; PG8_MMA(1, 0, At, B0); PG8_MMA(1, 1, At, B1); PG8_BAR; PG8_SCHED;
;             PG8_LDB(B0, 1, 0); PG8_LDB(B1, 1, 1); PG8_SCHED; PG8_LDA(At, 1, 0); PG8_STAGE(PG8_SA(0, 1), a2 + hstepA, voffA);
;             PG8_WAIT_V(8); PG8_WAIT_L(0); PG8_BAR; PG8_MMA(0, 0, At, B0); PG8_MMA(0, 1, At, B1); PG8_BAR; PG8_SCHED;
	v_mfma_f32_16x16x32_bf16 v[62:65], v[130:133], v[188:191], v[62:65]
	v_mfma_f32_16x16x32_bf16 v[58:61], v[152:155], v[188:191], v[58:61]
	v_mfma_f32_16x16x32_bf16 v[46:49], v[130:133], v[218:221], v[46:49]
	v_mfma_f32_16x16x32_bf16 v[42:45], v[152:155], v[218:221], v[42:45]
	v_mfma_f32_16x16x32_bf16 v[30:33], v[130:133], v[226:229], v[30:33]
	v_mfma_f32_16x16x32_bf16 v[26:29], v[152:155], v[226:229], v[26:29]
	v_mfma_f32_16x16x32_bf16 v[14:17], v[130:133], v[234:237], v[14:17]
	v_mfma_f32_16x16x32_bf16 v[10:13], v[152:155], v[234:237], v[10:13]
	v_mfma_f32_16x16x32_bf16 v[62:65], v[142:145], v[206:209], v[62:65]
	v_mfma_f32_16x16x32_bf16 v[58:61], v[156:159], v[206:209], v[58:61]
	v_mfma_f32_16x16x32_bf16 v[46:49], v[142:145], v[222:225], v[46:49]
	v_mfma_f32_16x16x32_bf16 v[42:45], v[156:159], v[222:225], v[42:45]
	v_mfma_f32_16x16x32_bf16 v[30:33], v[142:145], v[230:233], v[30:33]
	v_mfma_f32_16x16x32_bf16 v[26:29], v[156:159], v[230:233], v[26:29]
	v_mfma_f32_16x16x32_bf16 v[14:17], v[142:145], v[238:241], v[14:17]
	v_mfma_f32_16x16x32_bf16 v[10:13], v[156:159], v[238:241], v[10:13]
	v_mfma_f32_16x16x32_bf16 v[54:57], v[160:163], v[188:191], v[54:57]
	v_mfma_f32_16x16x32_bf16 v[50:53], v[168:171], v[188:191], v[50:53]
	v_mfma_f32_16x16x32_bf16 v[38:41], v[160:163], v[218:221], v[38:41]
	v_mfma_f32_16x16x32_bf16 v[34:37], v[168:171], v[218:221], v[34:37]
	v_mfma_f32_16x16x32_bf16 v[22:25], v[160:163], v[226:229], v[22:25]
	v_mfma_f32_16x16x32_bf16 v[18:21], v[168:171], v[226:229], v[18:21]
	v_mfma_f32_16x16x32_bf16 v[6:9], v[160:163], v[234:237], v[6:9]
	v_mfma_f32_16x16x32_bf16 v[2:5], v[168:171], v[234:237], v[2:5]
	v_mfma_f32_16x16x32_bf16 v[54:57], v[164:167], v[206:209], v[54:57]
	v_mfma_f32_16x16x32_bf16 v[50:53], v[172:175], v[206:209], v[50:53]
	v_mfma_f32_16x16x32_bf16 v[38:41], v[164:167], v[222:225], v[38:41]
	v_mfma_f32_16x16x32_bf16 v[34:37], v[172:175], v[222:225], v[34:37]
	v_mfma_f32_16x16x32_bf16 v[22:25], v[164:167], v[230:233], v[22:25]
	v_mfma_f32_16x16x32_bf16 v[18:21], v[172:175], v[230:233], v[18:21]
	v_mfma_f32_16x16x32_bf16 v[6:9], v[164:167], v[238:241], v[6:9]
	v_mfma_f32_16x16x32_bf16 v[2:5], v[172:175], v[238:241], v[2:5]
	s_barrier
	s_setprio 0
	s_add_i32 s51, 0, 0x18000
	s_add_i32 s52, 0, 0x1c000
	v_add_u32_e32 v156, s51, v149
	v_add_u32_e32 v172, s52, v149
	ds_read_b128 v[130:133], v156
	ds_read_b128 v[142:145], v156 offset:1024
	ds_read_b128 v[152:155], v156 offset:2048
	ds_read_b128 v[156:159], v156 offset:3072
	ds_read_b128 v[160:163], v172
	ds_read_b128 v[164:167], v172 offset:1024
	ds_read_b128 v[168:171], v172 offset:2048
	ds_read_b128 v[172:175], v172 offset:3072
	s_add_u32 s34, s34, 0x100000
	s_addc_u32 s35, s35, 0
	s_mov_b32 m0, s40
	v_lshl_add_u64 v[212:213], s[34:35], 0, v[134:135]
	ds_read_b128 v[188:191], v151 offset:32768
	ds_read_b128 v[206:209], v151 offset:33792
	ds_read_b128 v[218:221], v151 offset:34816
	ds_read_b128 v[222:225], v151 offset:35840
	ds_read_b128 v[226:229], v151 offset:36864
	ds_read_b128 v[230:233], v151 offset:37888
	ds_read_b128 v[234:237], v151 offset:38912
	ds_read_b128 v[238:241], v151 offset:39936
	global_load_lds_dwordx4 v[212:213], off
	s_mov_b32 m0, s41
	v_lshl_add_u64 v[212:213], s[34:35], 0, v[136:137]
	global_load_lds_dwordx4 v[212:213], off
	s_setprio 1
	s_waitcnt vmcnt(8) lgkmcnt(0)
	s_barrier
	v_mfma_f32_16x16x32_bf16 v[126:129], v[130:133], v[188:191], v[126:129]
	v_mfma_f32_16x16x32_bf16 v[122:125], v[152:155], v[188:191], v[122:125]
	v_mfma_f32_16x16x32_bf16 v[110:113], v[130:133], v[218:221], v[110:113]
	v_mfma_f32_16x16x32_bf16 v[106:109], v[152:155], v[218:221], v[106:109]
	v_mfma_f32_16x16x32_bf16 v[94:97], v[130:133], v[226:229], v[94:97]
	v_mfma_f32_16x16x32_bf16 v[90:93], v[152:155], v[226:229], v[90:93]
	v_mfma_f32_16x16x32_bf16 v[78:81], v[130:133], v[234:237], v[78:81]
	v_mfma_f32_16x16x32_bf16 v[74:77], v[152:155], v[234:237], v[74:77]
	v_mfma_f32_16x16x32_bf16 v[126:129], v[142:145], v[206:209], v[126:129]
	v_mfma_f32_16x16x32_bf16 v[122:125], v[156:159], v[206:209], v[122:125]
	v_mfma_f32_16x16x32_bf16 v[110:113], v[142:145], v[222:225], v[110:113]
	v_mfma_f32_16x16x32_bf16 v[106:109], v[156:159], v[222:225], v[106:109]
	v_mfma_f32_16x16x32_bf16 v[94:97], v[142:145], v[230:233], v[94:97]
	v_mfma_f32_16x16x32_bf16 v[90:93], v[156:159], v[230:233], v[90:93]
	v_mfma_f32_16x16x32_bf16 v[78:81], v[142:145], v[238:241], v[78:81]
	v_mfma_f32_16x16x32_bf16 v[74:77], v[156:159], v[238:241], v[74:77]
	v_mfma_f32_16x16x32_bf16 v[118:121], v[160:163], v[188:191], v[118:121]
	v_mfma_f32_16x16x32_bf16 v[114:117], v[168:171], v[188:191], v[114:117]
	v_mfma_f32_16x16x32_bf16 v[102:105], v[160:163], v[218:221], v[102:105]
	v_mfma_f32_16x16x32_bf16 v[98:101], v[168:171], v[218:221], v[98:101]
	v_mfma_f32_16x16x32_bf16 v[86:89], v[160:163], v[226:229], v[86:89]
	v_mfma_f32_16x16x32_bf16 v[82:85], v[168:171], v[226:229], v[82:85]
	v_mfma_f32_16x16x32_bf16 v[70:73], v[160:163], v[234:237], v[70:73]
	v_mfma_f32_16x16x32_bf16 v[66:69], v[168:171], v[234:237], v[66:69]
	v_mfma_f32_16x16x32_bf16 v[118:121], v[164:167], v[206:209], v[118:121]
	v_mfma_f32_16x16x32_bf16 v[114:117], v[172:175], v[206:209], v[114:117]
	v_mfma_f32_16x16x32_bf16 v[102:105], v[164:167], v[222:225], v[102:105]
	v_mfma_f32_16x16x32_bf16 v[98:101], v[172:175], v[222:225], v[98:101]
	v_mfma_f32_16x16x32_bf16 v[86:89], v[164:167], v[230:233], v[86:89]
	v_mfma_f32_16x16x32_bf16 v[82:85], v[172:175], v[230:233], v[82:85]
	v_mfma_f32_16x16x32_bf16 v[70:73], v[164:167], v[238:241], v[70:73]
	v_mfma_f32_16x16x32_bf16 v[66:69], v[172:175], v[238:241], v[66:69]
	s_barrier
; #define PG8_STAGE(bufoff, gbase, voff) do { _Pragma("unroll") for (int _i = 0; _i < 2; ++_i) \
;         __builtin_amdgcn_global_load_lds((const unsigned*)((const char*)(gbase) + (voff)[_i]), (PG8_LAS unsigned*)(lds + (bufoff) + ldsw + _i * 8192), 16, 0, 0); } while (0)
; #define PG8_LDA(dst, b, h) do { _Pragma("unroll") for (int m = 0; m < 4; ++m) _Pragma("unroll") for (int k = 0; k < 2; ++k) dst[m][k] = *(const PG8_LAS bf16x8*)(lds + PG8_SA(b, h) + aoff + m * 2048 + k * 1024); } while (0)
; #define PG8_MMA(ai, bj, At, Bt) do { __builtin_amdgcn_s_setprio(1); _Pragma("unroll") for (int m = 0; m < 4; ++m) _Pragma("unroll") for (int n = 0; n < 2; ++n) _Pragma("unroll") for (int k = 0; k < 2; ++k) \
;         acc[ai][bj][m][n] = __builtin_amdgcn_mfma_f32_16x16x32_bf16(Bt[n][k], At[m][k], acc[ai][bj][m][n], 0, 0, 0); __builtin_amdgcn_s_setprio(0); } while (0)
; #define PG8_WAIT_V(n) asm volatile("s_waitcnt vmcnt(" #n ")" ::: "memory")
; #define PG8_WAIT_L(n) asm volatile("s_waitcnt lgkmcnt(" #n ")" ::: "memory")
; #define PG8_BAR __builtin_amdgcn_s_barrier()
; #define PG8_SCHED __builtin_amdgcn_sched_barrier(0)
; template <class Epi, class Sched, bool ALIGN_EPI, int LMASK = -1, int LMASKB = LMASK>
; __device__ __forceinline__ void gemm_phase(PG8_LAS unsigned char* lds, const Gemm g, const Sched& S, const Epi& E) {
;     ...
;             PG8_LDA(At, 1, 1); PG8_STAGE(PG8_SB(1, 0), b3, voffB); PG8_STAGE(PG8_SB(1, 1), b3 + hstepB, voffB); PG8_STAGE(PG8_SA(1, 0), a3, voffA);
;             PG8_WAIT_V(8); PG8_WAIT_L(0); PG8_BAR; PG8_MMA(1, 0, At, B0); PG8_MMA(1, 1, At, B1); PG8_BAR; PG8_SCHED;
;         }
;         if constexpr (ALIGN_EPI) { if (wr == 0) PG8_BAR; }
	s_setprio 0
	s_add_i32 s34, s51, s38
	v_lshl_add_u64 v[146:147], v[146:147], 0, s[80:81]
	s_mov_b32 m0, s34
	ds_read_b128 v[188:191], v151 offset:49152
	ds_read_b128 v[206:209], v151 offset:50176
	ds_read_b128 v[218:221], v151 offset:51200
	ds_read_b128 v[222:225], v151 offset:52224
	ds_read_b128 v[226:229], v151 offset:53248
	ds_read_b128 v[230:233], v151 offset:54272
	ds_read_b128 v[234:237], v151 offset:55296
	ds_read_b128 v[238:241], v151 offset:56320
	global_load_lds_dwordx4 v[146:147], off
	s_add_i32 m0, s34, 0x2000
	s_add_u32 s30, s30, 0x100800
	v_lshl_add_u64 v[146:147], v[176:177], 0, s[80:81]
	s_addc_u32 s31, s31, 0
	s_add_i32 s34, s52, s38
	global_load_lds_dwordx4 v[146:147], off
	s_mov_b32 m0, s34
	v_lshl_add_u64 v[146:147], s[30:31], 0, v[134:135]
	global_load_lds_dwordx4 v[146:147], off
	s_add_i32 m0, s34, 0x2000
	v_lshl_add_u64 v[146:147], s[30:31], 0, v[136:137]
	global_load_lds_dwordx4 v[146:147], off
	s_mov_b32 m0, s42
	v_lshl_add_u64 v[146:147], v[194:195], 0, s[80:81]
	global_load_lds_dwordx4 v[146:147], off
	s_mov_b32 m0, s43
	v_lshl_add_u64 v[146:147], v[210:211], 0, s[80:81]
	global_load_lds_dwordx4 v[146:147], off
	s_setprio 1
	s_waitcnt vmcnt(8) lgkmcnt(0)
	s_barrier
	v_mfma_f32_16x16x32_bf16 v[62:65], v[130:133], v[188:191], v[62:65]
	v_mfma_f32_16x16x32_bf16 v[58:61], v[152:155], v[188:191], v[58:61]
	v_mfma_f32_16x16x32_bf16 v[46:49], v[130:133], v[218:221], v[46:49]
	v_mfma_f32_16x16x32_bf16 v[42:45], v[152:155], v[218:221], v[42:45]
	v_mfma_f32_16x16x32_bf16 v[30:33], v[130:133], v[226:229], v[30:33]
	v_mfma_f32_16x16x32_bf16 v[26:29], v[152:155], v[226:229], v[26:29]
	v_mfma_f32_16x16x32_bf16 v[14:17], v[130:133], v[234:237], v[14:17]
	v_mfma_f32_16x16x32_bf16 v[10:13], v[152:155], v[234:237], v[10:13]
	v_mfma_f32_16x16x32_bf16 v[62:65], v[142:145], v[206:209], v[62:65]
	v_mfma_f32_16x16x32_bf16 v[58:61], v[156:159], v[206:209], v[58:61]
	v_mfma_f32_16x16x32_bf16 v[46:49], v[142:145], v[222:225], v[46:49]
	v_mfma_f32_16x16x32_bf16 v[42:45], v[156:159], v[222:225], v[42:45]
	v_mfma_f32_16x16x32_bf16 v[30:33], v[142:145], v[230:233], v[30:33]
	v_mfma_f32_16x16x32_bf16 v[26:29], v[156:159], v[230:233], v[26:29]
	v_mfma_f32_16x16x32_bf16 v[14:17], v[142:145], v[238:241], v[14:17]
	v_mfma_f32_16x16x32_bf16 v[10:13], v[156:159], v[238:241], v[10:13]
	v_mfma_f32_16x16x32_bf16 v[54:57], v[160:163], v[188:191], v[54:57]
	v_mfma_f32_16x16x32_bf16 v[50:53], v[168:171], v[188:191], v[50:53]
	v_mfma_f32_16x16x32_bf16 v[38:41], v[160:163], v[218:221], v[38:41]
	v_mfma_f32_16x16x32_bf16 v[34:37], v[168:171], v[218:221], v[34:37]
	v_mfma_f32_16x16x32_bf16 v[22:25], v[160:163], v[226:229], v[22:25]
	v_mfma_f32_16x16x32_bf16 v[18:21], v[168:171], v[226:229], v[18:21]
	v_mfma_f32_16x16x32_bf16 v[6:9], v[160:163], v[234:237], v[6:9]
	v_mfma_f32_16x16x32_bf16 v[2:5], v[168:171], v[234:237], v[2:5]
	v_mfma_f32_16x16x32_bf16 v[54:57], v[164:167], v[206:209], v[54:57]
	v_mfma_f32_16x16x32_bf16 v[50:53], v[172:175], v[206:209], v[50:53]
	v_mfma_f32_16x16x32_bf16 v[38:41], v[164:167], v[222:225], v[38:41]
	v_mfma_f32_16x16x32_bf16 v[34:37], v[172:175], v[222:225], v[34:37]
	v_mfma_f32_16x16x32_bf16 v[22:25], v[164:167], v[230:233], v[22:25]
	v_mfma_f32_16x16x32_bf16 v[18:21], v[172:175], v[230:233], v[18:21]
	v_mfma_f32_16x16x32_bf16 v[6:9], v[164:167], v[238:241], v[6:9]
	v_mfma_f32_16x16x32_bf16 v[2:5], v[172:175], v[238:241], v[2:5]
	s_barrier
	s_setprio 0
	s_add_i32 s50, s50, 2
	s_add_u32 s28, s28, 0x1000
	s_addc_u32 s29, s29, 0
	s_add_u32 s48, s48, 0x1000
	s_addc_u32 s49, s49, 0
	s_cmp_gt_u32 s50, 61
	s_cbranch_scc0 .LBB0_580
	s_and_b64 vcc, exec, s[14:15]
	s_cbranch_vccz .LBB0_583
	s_barrier

; #define PG8_STAGE(bufoff, gbase, voff) do { _Pragma("unroll") for (int _i = 0; _i < 2; ++_i) \
;         __builtin_amdgcn_global_load_lds((const unsigned*)((const char*)(gbase) + (voff)[_i]), (PG8_LAS unsigned*)(lds + (bufoff) + ldsw + _i * 8192), 16, 0, 0); } while (0)
; #define PG8_LDA(dst, b, h) do { _Pragma("unroll") for (int m = 0; m < 4; ++m) _Pragma("unroll") for (int k = 0; k < 2; ++k) dst[m][k] = *(const PG8_LAS bf16x8*)(lds + PG8_SA(b, h) + aoff + m * 2048 + k * 1024); } while (0)
; #define PG8_LDB(dst, b, h) do { _Pragma("unroll") for (int n = 0; n < 2; ++n) _Pragma("unroll") for (int k = 0; k < 2; ++k) dst[n][k] = *(const PG8_LAS bf16x8*)(lds + PG8_SB(b, h) + boff + n * 2048 + k * 1024); } while (0)
; #define PG8_MMA(ai, bj, At, Bt) do { __builtin_amdgcn_s_setprio(1); _Pragma("unroll") for (int m = 0; m < 4; ++m) _Pragma("unroll") for (int n = 0; n < 2; ++n) _Pragma("unroll") for (int k = 0; k < 2; ++k) \
;         acc[ai][bj][m][n] = __builtin_amdgcn_mfma_f32_16x16x32_bf16(Bt[n][k], At[m][k], acc[ai][bj][m][n], 0, 0, 0); __builtin_amdgcn_s_setprio(0); } while (0)
; #define PG8_WAIT_V(n) asm volatile("s_waitcnt vmcnt(" #n ")" ::: "memory")
; #define PG8_WAIT_L(n) asm volatile("s_waitcnt lgkmcnt(" #n ")" ::: "memory")
; #define PG8_BAR __builtin_amdgcn_s_barrier()
; #define PG8_SCHED __builtin_amdgcn_sched_barrier(0)
; template <class Epi, class Sched, bool ALIGN_EPI, int LMASK = -1, int LMASKB = LMASK>
; __device__ __forceinline__ void gemm_phase(PG8_LAS unsigned char* lds, const Gemm g, const Sched& S, const Epi& E) {
;     ...
;             const bool last = (t == nt - 2);
;             const char* a1 = cA + (size_t)(t + 1) * kstepA;
;             const char* a2 = last ? nA : cA + (size_t)(t + 2) * kstepA; const char* b2 = last ? nB : cB + (size_t)(t + 2) * kstepB;
;             const char* a3 = a2 + kstepA; const char* b3 = b2 + kstepB;
;             PG8_LDB(B0, 0, 0); PG8_LDB(B1, 0, 1); PG8_SCHED; PG8_LDA(At, 0, 0); PG8_STAGE(PG8_SA(1, 1), a1 + hstepA, voffA);
;             PG8_WAIT_V(8); PG8_WAIT_L(0); PG8_BAR; PG8_MMA(0, 0, At, B0); PG8_MMA(0, 1, At, B1); PG8_BAR; PG8_SCHED;
;             PG8_LDA(At, 0, 1); PG8_STAGE(PG8_SB(0, 0), b2, voffB); PG8_STAGE(PG8_SB(0, 1), b2 + hstepB, voffB); PG8_STAGE(PG8_SA(0, 0), a2, voffA);
.LBB0_678:
	s_add_u32 s26, s24, 0xfff00800
	s_addc_u32 s27, s25, -1
	s_add_i32 s50, 0, 0x10000
	s_cmp_eq_u32 s49, 60
	s_cselect_b32 s29, s1, s27
	s_cselect_b32 s28, s2, s26
	s_cselect_b32 s27, s15, s48
	s_cselect_b32 s26, s17, s47
	s_add_i32 s52, 0, 0x14000
	v_add_u32_e32 v154, s50, v143
	v_add_u32_e32 v170, s52, v143
	ds_read_b128 v[138:141], v154
	ds_read_b128 v[146:149], v154 offset:1024
	ds_read_b128 v[150:153], v154 offset:2048
	ds_read_b128 v[154:157], v154 offset:3072
	ds_read_b128 v[158:161], v170
	ds_read_b128 v[162:165], v170 offset:1024
	ds_read_b128 v[166:169], v170 offset:2048
	ds_read_b128 v[170:173], v170 offset:3072
	v_lshl_add_u64 v[194:195], s[24:25], 0, v[134:135]
	s_add_i32 m0, s23, 0xc000
	ds_read_b128 v[174:177], v145
	ds_read_b128 v[188:191], v145 offset:1024
	ds_read_b128 v[206:209], v145 offset:2048
	ds_read_b128 v[218:221], v145 offset:3072
	ds_read_b128 v[222:225], v145 offset:4096
	ds_read_b128 v[226:229], v145 offset:5120
	ds_read_b128 v[230:233], v145 offset:6144
	ds_read_b128 v[234:237], v145 offset:7168
	global_load_lds_dwordx4 v[194:195], off
	s_add_i32 m0, s23, 0xe000
	v_lshl_add_u64 v[194:195], s[24:25], 0, v[136:137]
	global_load_lds_dwordx4 v[194:195], off
	s_setprio 1
	s_waitcnt vmcnt(8) lgkmcnt(0)
	s_barrier
	v_mfma_f32_16x16x32_bf16 v[126:129], v[138:141], v[174:177], v[126:129]
	v_mfma_f32_16x16x32_bf16 v[122:125], v[150:153], v[174:177], v[122:125]
	v_mfma_f32_16x16x32_bf16 v[110:113], v[138:141], v[206:209], v[110:113]
	v_mfma_f32_16x16x32_bf16 v[106:109], v[150:153], v[206:209], v[106:109]
	v_mfma_f32_16x16x32_bf16 v[94:97], v[138:141], v[222:225], v[94:97]
	v_mfma_f32_16x16x32_bf16 v[90:93], v[150:153], v[222:225], v[90:93]
	v_mfma_f32_16x16x32_bf16 v[78:81], v[138:141], v[230:233], v[78:81]
	v_mfma_f32_16x16x32_bf16 v[74:77], v[150:153], v[230:233], v[74:77]
	v_mfma_f32_16x16x32_bf16 v[126:129], v[146:149], v[188:191], v[126:129]
	v_mfma_f32_16x16x32_bf16 v[122:125], v[154:157], v[188:191], v[122:125]
	v_mfma_f32_16x16x32_bf16 v[110:113], v[146:149], v[218:221], v[110:113]
	v_mfma_f32_16x16x32_bf16 v[106:109], v[154:157], v[218:221], v[106:109]
	v_mfma_f32_16x16x32_bf16 v[94:97], v[146:149], v[226:229], v[94:97]
	v_mfma_f32_16x16x32_bf16 v[90:93], v[154:157], v[226:229], v[90:93]
	v_mfma_f32_16x16x32_bf16 v[78:81], v[146:149], v[234:237], v[78:81]
	v_mfma_f32_16x16x32_bf16 v[74:77], v[154:157], v[234:237], v[74:77]
	v_mfma_f32_16x16x32_bf16 v[118:121], v[158:161], v[174:177], v[118:121]
	v_mfma_f32_16x16x32_bf16 v[114:117], v[166:169], v[174:177], v[114:117]
	v_mfma_f32_16x16x32_bf16 v[102:105], v[158:161], v[206:209], v[102:105]
	v_mfma_f32_16x16x32_bf16 v[98:101], v[166:169], v[206:209], v[98:101]
	v_mfma_f32_16x16x32_bf16 v[86:89], v[158:161], v[222:225], v[86:89]
	v_mfma_f32_16x16x32_bf16 v[82:85], v[166:169], v[222:225], v[82:85]
	v_mfma_f32_16x16x32_bf16 v[70:73], v[158:161], v[230:233], v[70:73]
	v_mfma_f32_16x16x32_bf16 v[66:69], v[166:169], v[230:233], v[66:69]
	v_mfma_f32_16x16x32_bf16 v[118:121], v[162:165], v[188:191], v[118:121]
	v_mfma_f32_16x16x32_bf16 v[114:117], v[170:173], v[188:191], v[114:117]
	v_mfma_f32_16x16x32_bf16 v[102:105], v[162:165], v[218:221], v[102:105]
	v_mfma_f32_16x16x32_bf16 v[98:101], v[170:173], v[218:221], v[98:101]
	v_mfma_f32_16x16x32_bf16 v[86:89], v[162:165], v[226:229], v[86:89]
	v_mfma_f32_16x16x32_bf16 v[82:85], v[170:173], v[226:229], v[82:85]
	v_mfma_f32_16x16x32_bf16 v[70:73], v[162:165], v[234:237], v[70:73]
	v_mfma_f32_16x16x32_bf16 v[66:69], v[170:173], v[234:237], v[66:69]
	s_barrier
	s_setprio 0
	s_add_i32 s50, s50, s38
	v_lshl_add_u64 v[194:195], s[26:27], 0, v[130:131]
	s_mov_b32 m0, s50
	ds_read_b128 v[174:177], v145 offset:16384
	ds_read_b128 v[188:191], v145 offset:17408
	ds_read_b128 v[206:209], v145 offset:18432
	ds_read_b128 v[218:221], v145 offset:19456
	ds_read_b128 v[222:225], v145 offset:20480
	ds_read_b128 v[226:229], v145 offset:21504
	ds_read_b128 v[230:233], v145 offset:22528
	ds_read_b128 v[234:237], v145 offset:23552
	global_load_lds_dwordx4 v[194:195], off
	s_add_i32 m0, s50, 0x2000
	s_add_u32 s50, s26, 0x100000
	v_lshl_add_u64 v[210:211], s[26:27], 0, v[132:133]
	s_addc_u32 s51, s27, 0
	s_add_i32 s52, s52, s38
	global_load_lds_dwordx4 v[210:211], off
	v_lshl_add_u64 v[212:213], s[50:51], 0, v[130:131]
	s_mov_b32 m0, s52
	v_lshl_add_u64 v[238:239], s[28:29], 0, v[132:133]
	global_load_lds_dwordx4 v[212:213], off
	s_add_i32 m0, s52, 0x2000
	v_lshl_add_u64 v[212:213], s[50:51], 0, v[132:133]
	global_load_lds_dwordx4 v[212:213], off
	s_mov_b32 m0, s23
	v_lshl_add_u64 v[212:213], s[28:29], 0, v[130:131]
	global_load_lds_dwordx4 v[212:213], off
	s_mov_b32 m0, s39
	s_nop 0
	global_load_lds_dwordx4 v[238:239], off
	s_setprio 1
	s_waitcnt vmcnt(8) lgkmcnt(0)
	s_barrier
; #define PG8_STAGE(bufoff, gbase, voff) do { _Pragma("unroll") for (int _i = 0; _i < 2; ++_i) \
;         __builtin_amdgcn_global_load_lds((const unsigned*)((const char*)(gbase) + (voff)[_i]), (PG8_LAS unsigned*)(lds + (bufoff) + ldsw + _i * 8192), 16, 0, 0); } while (0)
; #define PG8_LDA(dst, b, h) do { _Pragma("unroll") for (int m = 0; m < 4; ++m) _Pragma("unroll") for (int k = 0; k < 2; ++k) dst[m][k] = *(const PG8_LAS bf16x8*)(lds + PG8_SA(b, h) + aoff + m * 2048 + k * 1024); } while (0)
; #define PG8_LDB(dst, b, h) do { _Pragma("unroll") for (int n = 0; n < 2; ++n) _Pragma("unroll") for (int k = 0; k < 2; ++k) dst[n][k] = *(const PG8_LAS bf16x8*)(lds + PG8_SB(b, h) + boff + n * 2048 + k * 1024); } while (0)
; #define PG8_MMA(ai, bj, At, Bt) do { __builtin_amdgcn_s_setprio(1); _Pragma("unroll") for (int m = 0; m < 4; ++m) _Pragma("unroll") for (int n = 0; n < 2; ++n) _Pragma("unroll") for (int k = 0; k < 2; ++k) \
;         acc[ai][bj][m][n] = __builtin_amdgcn_mfma_f32_16x16x32_bf16(Bt[n][k], At[m][k], acc[ai][bj][m][n], 0, 0, 0); __builtin_amdgcn_s_setprio(0); } while (0)
; #define PG8_WAIT_V(n) asm volatile("s_waitcnt vmcnt(" #n ")" ::: "memory")
; #define PG8_WAIT_L(n) asm volatile("s_waitcnt lgkmcnt(" #n ")" ::: "memory")
; #define PG8_BAR __builtin_amdgcn_s_barrier()
; #define PG8_SCHED __builtin_amdgcn_sched_barrier(0)
; template <class Epi, class Sched, bool ALIGN_EPI, int LMASK = -1, int LMASKB = LMASK>
; __device__ __forceinline__ void gemm_phase(PG8_LAS unsigned char* lds, const Gemm g, const Sched& S, const Epi& E) {
;     ...
;             PG8_WAIT_V(8); PG8_WAIT_L(0); PG8_BAR; PG8_MMA(1, 0, At, B0); PG8_MMA(1, 1, At, B1); PG8_BAR; PG8_SCHED;
;             PG8_LDB(B0, 1, 0); PG8_LDB(B1, 1, 1); PG8_SCHED; PG8_LDA(At, 1, 0); PG8_STAGE(PG8_SA(0, 1), a2 + hstepA, voffA);
;             PG8_WAIT_V(8); PG8_WAIT_L(0); PG8_BAR; PG8_MMA(0, 0, At, B0); PG8_MMA(0, 1, At, B1); PG8_BAR; PG8_SCHED;
	v_mfma_f32_16x16x32_bf16 v[62:65], v[138:141], v[174:177], v[62:65]
	v_mfma_f32_16x16x32_bf16 v[58:61], v[150:153], v[174:177], v[58:61]
	v_mfma_f32_16x16x32_bf16 v[46:49], v[138:141], v[206:209], v[46:49]
	v_mfma_f32_16x16x32_bf16 v[42:45], v[150:153], v[206:209], v[42:45]
	v_mfma_f32_16x16x32_bf16 v[30:33], v[138:141], v[222:225], v[30:33]
	v_mfma_f32_16x16x32_bf16 v[26:29], v[150:153], v[222:225], v[26:29]
	v_mfma_f32_16x16x32_bf16 v[14:17], v[138:141], v[230:233], v[14:17]
	v_mfma_f32_16x16x32_bf16 v[10:13], v[150:153], v[230:233], v[10:13]
	v_mfma_f32_16x16x32_bf16 v[62:65], v[146:149], v[188:191], v[62:65]
	v_mfma_f32_16x16x32_bf16 v[58:61], v[154:157], v[188:191], v[58:61]
	v_mfma_f32_16x16x32_bf16 v[46:49], v[146:149], v[218:221], v[46:49]
	v_mfma_f32_16x16x32_bf16 v[42:45], v[154:157], v[218:221], v[42:45]
	v_mfma_f32_16x16x32_bf16 v[30:33], v[146:149], v[226:229], v[30:33]
	v_mfma_f32_16x16x32_bf16 v[26:29], v[154:157], v[226:229], v[26:29]
	v_mfma_f32_16x16x32_bf16 v[14:17], v[146:149], v[234:237], v[14:17]
	v_mfma_f32_16x16x32_bf16 v[10:13], v[154:157], v[234:237], v[10:13]
	v_mfma_f32_16x16x32_bf16 v[54:57], v[158:161], v[174:177], v[54:57]
	v_mfma_f32_16x16x32_bf16 v[50:53], v[166:169], v[174:177], v[50:53]
	v_mfma_f32_16x16x32_bf16 v[38:41], v[158:161], v[206:209], v[38:41]
	v_mfma_f32_16x16x32_bf16 v[34:37], v[166:169], v[206:209], v[34:37]
	v_mfma_f32_16x16x32_bf16 v[22:25], v[158:161], v[222:225], v[22:25]
	v_mfma_f32_16x16x32_bf16 v[18:21], v[166:169], v[222:225], v[18:21]
	v_mfma_f32_16x16x32_bf16 v[6:9], v[158:161], v[230:233], v[6:9]
	v_mfma_f32_16x16x32_bf16 v[2:5], v[166:169], v[230:233], v[2:5]
	v_mfma_f32_16x16x32_bf16 v[54:57], v[162:165], v[188:191], v[54:57]
	v_mfma_f32_16x16x32_bf16 v[50:53], v[170:173], v[188:191], v[50:53]
	v_mfma_f32_16x16x32_bf16 v[38:41], v[162:165], v[218:221], v[38:41]
	v_mfma_f32_16x16x32_bf16 v[34:37], v[170:173], v[218:221], v[34:37]
	v_mfma_f32_16x16x32_bf16 v[22:25], v[162:165], v[226:229], v[22:25]
	v_mfma_f32_16x16x32_bf16 v[18:21], v[170:173], v[226:229], v[18:21]
	v_mfma_f32_16x16x32_bf16 v[6:9], v[162:165], v[234:237], v[6:9]
	v_mfma_f32_16x16x32_bf16 v[2:5], v[170:173], v[234:237], v[2:5]
	s_barrier
	s_setprio 0
	s_add_i32 s50, 0, 0x18000
	s_add_i32 s51, 0, 0x1c000
	v_add_u32_e32 v154, s50, v143
	v_add_u32_e32 v170, s51, v143
	ds_read_b128 v[138:141], v154
	ds_read_b128 v[146:149], v154 offset:1024
	ds_read_b128 v[150:153], v154 offset:2048
	ds_read_b128 v[154:157], v154 offset:3072
	ds_read_b128 v[158:161], v170
	ds_read_b128 v[162:165], v170 offset:1024
	ds_read_b128 v[166:169], v170 offset:2048
	ds_read_b128 v[170:173], v170 offset:3072
	s_add_u32 s28, s28, 0x100000
	s_addc_u32 s29, s29, 0
	s_mov_b32 m0, s40
	v_lshl_add_u64 v[240:241], s[28:29], 0, v[130:131]
	ds_read_b128 v[174:177], v145 offset:32768
	ds_read_b128 v[188:191], v145 offset:33792
	ds_read_b128 v[206:209], v145 offset:34816
	ds_read_b128 v[218:221], v145 offset:35840
	ds_read_b128 v[222:225], v145 offset:36864
	ds_read_b128 v[226:229], v145 offset:37888
	ds_read_b128 v[230:233], v145 offset:38912
	ds_read_b128 v[234:237], v145 offset:39936
	global_load_lds_dwordx4 v[240:241], off
	s_mov_b32 m0, s41
	v_lshl_add_u64 v[240:241], s[28:29], 0, v[132:133]
	global_load_lds_dwordx4 v[240:241], off
	s_setprio 1
	s_waitcnt vmcnt(8) lgkmcnt(0)
	s_barrier
	v_mfma_f32_16x16x32_bf16 v[126:129], v[138:141], v[174:177], v[126:129]
	v_mfma_f32_16x16x32_bf16 v[122:125], v[150:153], v[174:177], v[122:125]
	v_mfma_f32_16x16x32_bf16 v[110:113], v[138:141], v[206:209], v[110:113]
	v_mfma_f32_16x16x32_bf16 v[106:109], v[150:153], v[206:209], v[106:109]
	v_mfma_f32_16x16x32_bf16 v[94:97], v[138:141], v[222:225], v[94:97]
	v_mfma_f32_16x16x32_bf16 v[90:93], v[150:153], v[222:225], v[90:93]
	v_mfma_f32_16x16x32_bf16 v[78:81], v[138:141], v[230:233], v[78:81]
	v_mfma_f32_16x16x32_bf16 v[74:77], v[150:153], v[230:233], v[74:77]
	v_mfma_f32_16x16x32_bf16 v[126:129], v[146:149], v[188:191], v[126:129]
	v_mfma_f32_16x16x32_bf16 v[122:125], v[154:157], v[188:191], v[122:125]
	v_mfma_f32_16x16x32_bf16 v[110:113], v[146:149], v[218:221], v[110:113]
	v_mfma_f32_16x16x32_bf16 v[106:109], v[154:157], v[218:221], v[106:109]
	v_mfma_f32_16x16x32_bf16 v[94:97], v[146:149], v[226:229], v[94:97]
	v_mfma_f32_16x16x32_bf16 v[90:93], v[154:157], v[226:229], v[90:93]
	v_mfma_f32_16x16x32_bf16 v[78:81], v[146:149], v[234:237], v[78:81]
	v_mfma_f32_16x16x32_bf16 v[74:77], v[154:157], v[234:237], v[74:77]
	v_mfma_f32_16x16x32_bf16 v[118:121], v[158:161], v[174:177], v[118:121]
	v_mfma_f32_16x16x32_bf16 v[114:117], v[166:169], v[174:177], v[114:117]
	v_mfma_f32_16x16x32_bf16 v[102:105], v[158:161], v[206:209], v[102:105]
	v_mfma_f32_16x16x32_bf16 v[98:101], v[166:169], v[206:209], v[98:101]
	v_mfma_f32_16x16x32_bf16 v[86:89], v[158:161], v[222:225], v[86:89]
	v_mfma_f32_16x16x32_bf16 v[82:85], v[166:169], v[222:225], v[82:85]
	v_mfma_f32_16x16x32_bf16 v[70:73], v[158:161], v[230:233], v[70:73]
	v_mfma_f32_16x16x32_bf16 v[66:69], v[166:169], v[230:233], v[66:69]
	v_mfma_f32_16x16x32_bf16 v[118:121], v[162:165], v[188:191], v[118:121]
	v_mfma_f32_16x16x32_bf16 v[114:117], v[170:173], v[188:191], v[114:117]
	v_mfma_f32_16x16x32_bf16 v[102:105], v[162:165], v[218:221], v[102:105]
	v_mfma_f32_16x16x32_bf16 v[98:101], v[170:173], v[218:221], v[98:101]
	v_mfma_f32_16x16x32_bf16 v[86:89], v[162:165], v[226:229], v[86:89]
	v_mfma_f32_16x16x32_bf16 v[82:85], v[170:173], v[226:229], v[82:85]
	v_mfma_f32_16x16x32_bf16 v[70:73], v[162:165], v[234:237], v[70:73]
	v_mfma_f32_16x16x32_bf16 v[66:69], v[170:173], v[234:237], v[66:69]
	s_barrier
; #define PG8_STAGE(bufoff, gbase, voff) do { _Pragma("unroll") for (int _i = 0; _i < 2; ++_i) \
;         __builtin_amdgcn_global_load_lds((const unsigned*)((const char*)(gbase) + (voff)[_i]), (PG8_LAS unsigned*)(lds + (bufoff) + ldsw + _i * 8192), 16, 0, 0); } while (0)
; #define PG8_LDA(dst, b, h) do { _Pragma("unroll") for (int m = 0; m < 4; ++m) _Pragma("unroll") for (int k = 0; k < 2; ++k) dst[m][k] = *(const PG8_LAS bf16x8*)(lds + PG8_SA(b, h) + aoff + m * 2048 + k * 1024); } while (0)
; #define PG8_MMA(ai, bj, At, Bt) do { __builtin_amdgcn_s_setprio(1); _Pragma("unroll") for (int m = 0; m < 4; ++m) _Pragma("unroll") for (int n = 0; n < 2; ++n) _Pragma("unroll") for (int k = 0; k < 2; ++k) \
;         acc[ai][bj][m][n] = __builtin_amdgcn_mfma_f32_16x16x32_bf16(Bt[n][k], At[m][k], acc[ai][bj][m][n], 0, 0, 0); __builtin_amdgcn_s_setprio(0); } while (0)
; #define PG8_WAIT_V(n) asm volatile("s_waitcnt vmcnt(" #n ")" ::: "memory")
; #define PG8_WAIT_L(n) asm volatile("s_waitcnt lgkmcnt(" #n ")" ::: "memory")
; #define PG8_BAR __builtin_amdgcn_s_barrier()
; #define PG8_SCHED __builtin_amdgcn_sched_barrier(0)
; template <class Epi, class Sched, bool ALIGN_EPI, int LMASK = -1, int LMASKB = LMASK>
; __device__ __forceinline__ void gemm_phase(PG8_LAS unsigned char* lds, const Gemm g, const Sched& S, const Epi& E) {
;     ...
;             PG8_LDA(At, 1, 1); PG8_STAGE(PG8_SB(1, 0), b3, voffB); PG8_STAGE(PG8_SB(1, 1), b3 + hstepB, voffB); PG8_STAGE(PG8_SA(1, 0), a3, voffA);
;             PG8_WAIT_V(8); PG8_WAIT_L(0); PG8_BAR; PG8_MMA(1, 0, At, B0); PG8_MMA(1, 1, At, B1); PG8_BAR; PG8_SCHED;
;         }
;         if constexpr (ALIGN_EPI) { if (wr == 0) PG8_BAR; }
	s_setprio 0
	s_add_i32 s28, s50, s38
	v_lshl_add_u64 v[194:195], v[194:195], 0, s[80:81]
	s_mov_b32 m0, s28
	ds_read_b128 v[174:177], v145 offset:49152
	ds_read_b128 v[188:191], v145 offset:50176
	ds_read_b128 v[206:209], v145 offset:51200
	ds_read_b128 v[218:221], v145 offset:52224
	ds_read_b128 v[222:225], v145 offset:53248
	ds_read_b128 v[226:229], v145 offset:54272
	ds_read_b128 v[230:233], v145 offset:55296
	ds_read_b128 v[234:237], v145 offset:56320
	global_load_lds_dwordx4 v[194:195], off
	s_add_i32 m0, s28, 0x2000
	s_add_u32 s26, s26, 0x100800
	v_lshl_add_u64 v[194:195], v[210:211], 0, s[80:81]
	s_addc_u32 s27, s27, 0
	s_add_i32 s28, s51, s38
	global_load_lds_dwordx4 v[194:195], off
	s_mov_b32 m0, s28
	v_lshl_add_u64 v[194:195], s[26:27], 0, v[130:131]
	global_load_lds_dwordx4 v[194:195], off
	s_add_i32 m0, s28, 0x2000
	v_lshl_add_u64 v[194:195], s[26:27], 0, v[132:133]
	global_load_lds_dwordx4 v[194:195], off
	s_mov_b32 m0, s42
	v_lshl_add_u64 v[194:195], v[212:213], 0, s[80:81]
	global_load_lds_dwordx4 v[194:195], off
	s_mov_b32 m0, s43
	v_lshl_add_u64 v[194:195], v[238:239], 0, s[80:81]
	global_load_lds_dwordx4 v[194:195], off
	s_setprio 1
	s_waitcnt vmcnt(8) lgkmcnt(0)
	s_barrier
	v_mfma_f32_16x16x32_bf16 v[62:65], v[138:141], v[174:177], v[62:65]
	v_mfma_f32_16x16x32_bf16 v[58:61], v[150:153], v[174:177], v[58:61]
	v_mfma_f32_16x16x32_bf16 v[46:49], v[138:141], v[206:209], v[46:49]
	v_mfma_f32_16x16x32_bf16 v[42:45], v[150:153], v[206:209], v[42:45]
	v_mfma_f32_16x16x32_bf16 v[30:33], v[138:141], v[222:225], v[30:33]
	v_mfma_f32_16x16x32_bf16 v[26:29], v[150:153], v[222:225], v[26:29]
	v_mfma_f32_16x16x32_bf16 v[14:17], v[138:141], v[230:233], v[14:17]
	v_mfma_f32_16x16x32_bf16 v[10:13], v[150:153], v[230:233], v[10:13]
	v_mfma_f32_16x16x32_bf16 v[62:65], v[146:149], v[188:191], v[62:65]
	v_mfma_f32_16x16x32_bf16 v[58:61], v[154:157], v[188:191], v[58:61]
	v_mfma_f32_16x16x32_bf16 v[46:49], v[146:149], v[218:221], v[46:49]
	v_mfma_f32_16x16x32_bf16 v[42:45], v[154:157], v[218:221], v[42:45]
	v_mfma_f32_16x16x32_bf16 v[30:33], v[146:149], v[226:229], v[30:33]
	v_mfma_f32_16x16x32_bf16 v[26:29], v[154:157], v[226:229], v[26:29]
	v_mfma_f32_16x16x32_bf16 v[14:17], v[146:149], v[234:237], v[14:17]
	v_mfma_f32_16x16x32_bf16 v[10:13], v[154:157], v[234:237], v[10:13]
	v_mfma_f32_16x16x32_bf16 v[54:57], v[158:161], v[174:177], v[54:57]
	v_mfma_f32_16x16x32_bf16 v[50:53], v[166:169], v[174:177], v[50:53]
	v_mfma_f32_16x16x32_bf16 v[38:41], v[158:161], v[206:209], v[38:41]
	v_mfma_f32_16x16x32_bf16 v[34:37], v[166:169], v[206:209], v[34:37]
	v_mfma_f32_16x16x32_bf16 v[22:25], v[158:161], v[222:225], v[22:25]
	v_mfma_f32_16x16x32_bf16 v[18:21], v[166:169], v[222:225], v[18:21]
	v_mfma_f32_16x16x32_bf16 v[6:9], v[158:161], v[230:233], v[6:9]
	v_mfma_f32_16x16x32_bf16 v[2:5], v[166:169], v[230:233], v[2:5]
	v_mfma_f32_16x16x32_bf16 v[54:57], v[162:165], v[188:191], v[54:57]
	v_mfma_f32_16x16x32_bf16 v[50:53], v[170:173], v[188:191], v[50:53]
	v_mfma_f32_16x16x32_bf16 v[38:41], v[162:165], v[218:221], v[38:41]
	v_mfma_f32_16x16x32_bf16 v[34:37], v[170:173], v[218:221], v[34:37]
	v_mfma_f32_16x16x32_bf16 v[22:25], v[162:165], v[226:229], v[22:25]
	v_mfma_f32_16x16x32_bf16 v[18:21], v[170:173], v[226:229], v[18:21]
	v_mfma_f32_16x16x32_bf16 v[6:9], v[162:165], v[234:237], v[6:9]
	v_mfma_f32_16x16x32_bf16 v[2:5], v[170:173], v[234:237], v[2:5]
	s_barrier
	s_setprio 0
	s_add_i32 s49, s49, 2
	s_add_u32 s24, s24, 0x1000
	s_addc_u32 s25, s25, 0
	s_add_u32 s47, s47, 0x1000
	s_addc_u32 s48, s48, 0
	s_cmp_gt_u32 s49, 61
	s_cbranch_scc0 .LBB0_678
	s_and_b64 vcc, exec, s[12:13]
	s_cbranch_vccz .LBB0_681
	s_barrier

; #define PG8_STAGE(bufoff, gbase, voff) do { _Pragma("unroll") for (int _i = 0; _i < 2; ++_i) \
;         __builtin_amdgcn_global_load_lds((const unsigned*)((const char*)(gbase) + (voff)[_i]), (PG8_LAS unsigned*)(lds + (bufoff) + ldsw + _i * 8192), 16, 0, 0); } while (0)
; #define PG8_LDA(dst, b, h) do { _Pragma("unroll") for (int m = 0; m < 4; ++m) _Pragma("unroll") for (int k = 0; k < 2; ++k) dst[m][k] = *(const PG8_LAS bf16x8*)(lds + PG8_SA(b, h) + aoff + m * 2048 + k * 1024); } while (0)
; #define PG8_LDB(dst, b, h) do { _Pragma("unroll") for (int n = 0; n < 2; ++n) _Pragma("unroll") for (int k = 0; k < 2; ++k) dst[n][k] = *(const PG8_LAS bf16x8*)(lds + PG8_SB(b, h) + boff + n * 2048 + k * 1024); } while (0)
; #define PG8_MMA(ai, bj, At, Bt) do { __builtin_amdgcn_s_setprio(1); _Pragma("unroll") for (int m = 0; m < 4; ++m) _Pragma("unroll") for (int n = 0; n < 2; ++n) _Pragma("unroll") for (int k = 0; k < 2; ++k) \
;         acc[ai][bj][m][n] = __builtin_amdgcn_mfma_f32_16x16x32_bf16(Bt[n][k], At[m][k], acc[ai][bj][m][n], 0, 0, 0); __builtin_amdgcn_s_setprio(0); } while (0)
; #define PG8_WAIT_V(n) asm volatile("s_waitcnt vmcnt(" #n ")" ::: "memory")
; #define PG8_WAIT_L(n) asm volatile("s_waitcnt lgkmcnt(" #n ")" ::: "memory")
; #define PG8_BAR __builtin_amdgcn_s_barrier()
; #define PG8_SCHED __builtin_amdgcn_sched_barrier(0)
; template <class Epi, class Sched, bool ALIGN_EPI, int LMASK = -1, int LMASKB = LMASK>
; __device__ __forceinline__ void gemm_phase(PG8_LAS unsigned char* lds, const Gemm g, const Sched& S, const Epi& E) {
;     ...
;             const bool last = (t == nt - 2);
;             const char* a1 = cA + (size_t)(t + 1) * kstepA;
;             const char* a2 = last ? nA : cA + (size_t)(t + 2) * kstepA; const char* b2 = last ? nB : cB + (size_t)(t + 2) * kstepB;
;             const char* a3 = a2 + kstepA; const char* b3 = b2 + kstepB;
;             PG8_LDB(B0, 0, 0); PG8_LDB(B1, 0, 1); PG8_SCHED; PG8_LDA(At, 0, 0); PG8_STAGE(PG8_SA(1, 1), a1 + hstepA, voffA);
;             PG8_WAIT_V(8); PG8_WAIT_L(0); PG8_BAR; PG8_MMA(0, 0, At, B0); PG8_MMA(0, 1, At, B1); PG8_BAR; PG8_SCHED;
;             PG8_LDA(At, 0, 1); PG8_STAGE(PG8_SB(0, 0), b2, voffB); PG8_STAGE(PG8_SB(0, 1), b2 + hstepB, voffB); PG8_STAGE(PG8_SA(0, 0), a2, voffA);
.LBB0_761:
	s_add_u32 s2, s28, 0xffc00800
	s_addc_u32 s3, s29, -1
	s_add_i32 s51, 0, 0x10000
	s_cmpk_eq_i32 s50, 0xfc
	s_cselect_b32 s31, s19, s3
	s_cselect_b32 s30, s46, s2
	v_add_u32_e32 v146, s51, v149
	s_cselect_b32 s3, s17, s49
	s_cselect_b32 s2, s47, s48
	s_add_i32 s54, 0, 0x14000
	ds_read_b128 v[130:133], v146
	ds_read_b128 v[142:145], v146 offset:1024
	ds_read_b128 v[152:155], v146 offset:2048
	ds_read_b128 v[156:159], v146 offset:3072
	v_add_u32_e32 v146, s54, v149
	ds_read_b128 v[160:163], v146
	ds_read_b128 v[164:167], v146 offset:1024
	ds_read_b128 v[168:171], v146 offset:2048
	ds_read_b128 v[172:175], v146 offset:3072
	v_lshl_add_u64 v[146:147], s[28:29], 0, v[138:139]
	s_add_i32 m0, s25, 0xc000
	ds_read_b128 v[188:191], v151
	ds_read_b128 v[206:209], v151 offset:1024
	ds_read_b128 v[218:221], v151 offset:2048
	ds_read_b128 v[222:225], v151 offset:3072
	ds_read_b128 v[226:229], v151 offset:4096
	ds_read_b128 v[230:233], v151 offset:5120
	ds_read_b128 v[234:237], v151 offset:6144
	ds_read_b128 v[238:241], v151 offset:7168
	global_load_lds_dwordx4 v[146:147], off
	s_add_i32 m0, s25, 0xe000
	v_lshl_add_u64 v[146:147], s[28:29], 0, v[140:141]
	global_load_lds_dwordx4 v[146:147], off
	s_setprio 1
	s_waitcnt vmcnt(8) lgkmcnt(0)
	s_barrier
	v_mfma_f32_16x16x32_bf16 v[126:129], v[130:133], v[188:191], v[126:129]
	v_mfma_f32_16x16x32_bf16 v[122:125], v[152:155], v[188:191], v[122:125]
	v_mfma_f32_16x16x32_bf16 v[110:113], v[130:133], v[218:221], v[110:113]
	v_mfma_f32_16x16x32_bf16 v[106:109], v[152:155], v[218:221], v[106:109]
	v_mfma_f32_16x16x32_bf16 v[94:97], v[130:133], v[226:229], v[94:97]
	v_mfma_f32_16x16x32_bf16 v[90:93], v[152:155], v[226:229], v[90:93]
	v_mfma_f32_16x16x32_bf16 v[78:81], v[130:133], v[234:237], v[78:81]
	v_mfma_f32_16x16x32_bf16 v[74:77], v[152:155], v[234:237], v[74:77]
	v_mfma_f32_16x16x32_bf16 v[126:129], v[142:145], v[206:209], v[126:129]
	v_mfma_f32_16x16x32_bf16 v[122:125], v[156:159], v[206:209], v[122:125]
	v_mfma_f32_16x16x32_bf16 v[110:113], v[142:145], v[222:225], v[110:113]
	v_mfma_f32_16x16x32_bf16 v[106:109], v[156:159], v[222:225], v[106:109]
	v_mfma_f32_16x16x32_bf16 v[94:97], v[142:145], v[230:233], v[94:97]
	v_mfma_f32_16x16x32_bf16 v[90:93], v[156:159], v[230:233], v[90:93]
	v_mfma_f32_16x16x32_bf16 v[78:81], v[142:145], v[238:241], v[78:81]
	v_mfma_f32_16x16x32_bf16 v[74:77], v[156:159], v[238:241], v[74:77]
	v_mfma_f32_16x16x32_bf16 v[118:121], v[160:163], v[188:191], v[118:121]
	v_mfma_f32_16x16x32_bf16 v[114:117], v[168:171], v[188:191], v[114:117]
	v_mfma_f32_16x16x32_bf16 v[102:105], v[160:163], v[218:221], v[102:105]
	v_mfma_f32_16x16x32_bf16 v[98:101], v[168:171], v[218:221], v[98:101]
	v_mfma_f32_16x16x32_bf16 v[86:89], v[160:163], v[226:229], v[86:89]
	v_mfma_f32_16x16x32_bf16 v[82:85], v[168:171], v[226:229], v[82:85]
	v_mfma_f32_16x16x32_bf16 v[70:73], v[160:163], v[234:237], v[70:73]
	v_mfma_f32_16x16x32_bf16 v[66:69], v[168:171], v[234:237], v[66:69]
	v_mfma_f32_16x16x32_bf16 v[118:121], v[164:167], v[206:209], v[118:121]
	v_mfma_f32_16x16x32_bf16 v[114:117], v[172:175], v[206:209], v[114:117]
	v_mfma_f32_16x16x32_bf16 v[102:105], v[164:167], v[222:225], v[102:105]
	v_mfma_f32_16x16x32_bf16 v[98:101], v[172:175], v[222:225], v[98:101]
	v_mfma_f32_16x16x32_bf16 v[86:89], v[164:167], v[230:233], v[86:89]
	v_mfma_f32_16x16x32_bf16 v[82:85], v[172:175], v[230:233], v[82:85]
	v_mfma_f32_16x16x32_bf16 v[70:73], v[164:167], v[238:241], v[70:73]
	v_mfma_f32_16x16x32_bf16 v[66:69], v[172:175], v[238:241], v[66:69]
	s_barrier
	s_setprio 0
	s_add_i32 s51, s51, s38
	v_lshl_add_u64 v[146:147], s[2:3], 0, v[134:135]
	s_mov_b32 m0, s51
	ds_read_b128 v[188:191], v151 offset:16384
	ds_read_b128 v[206:209], v151 offset:17408
	ds_read_b128 v[218:221], v151 offset:18432
	ds_read_b128 v[222:225], v151 offset:19456
	ds_read_b128 v[226:229], v151 offset:20480
	ds_read_b128 v[230:233], v151 offset:21504
	ds_read_b128 v[234:237], v151 offset:22528
	ds_read_b128 v[238:241], v151 offset:23552
	global_load_lds_dwordx4 v[146:147], off
	s_add_i32 m0, s51, 0x2000
	s_add_u32 s52, s2, 0x400000
	v_lshl_add_u64 v[176:177], s[2:3], 0, v[136:137]
	s_addc_u32 s53, s3, 0
	s_add_i32 s51, s54, s38
	global_load_lds_dwordx4 v[176:177], off
	v_lshl_add_u64 v[194:195], s[52:53], 0, v[134:135]
	s_mov_b32 m0, s51
	v_lshl_add_u64 v[210:211], s[30:31], 0, v[136:137]
	global_load_lds_dwordx4 v[194:195], off
	s_add_i32 m0, s51, 0x2000
	v_lshl_add_u64 v[194:195], s[52:53], 0, v[136:137]
	global_load_lds_dwordx4 v[194:195], off
	s_mov_b32 m0, s25
	v_lshl_add_u64 v[194:195], s[30:31], 0, v[134:135]
	global_load_lds_dwordx4 v[194:195], off
	s_mov_b32 m0, s27
	s_nop 0
	global_load_lds_dwordx4 v[210:211], off
	s_setprio 1
	s_waitcnt vmcnt(8) lgkmcnt(0)
	s_barrier
; #define PG8_STAGE(bufoff, gbase, voff) do { _Pragma("unroll") for (int _i = 0; _i < 2; ++_i) \
;         __builtin_amdgcn_global_load_lds((const unsigned*)((const char*)(gbase) + (voff)[_i]), (PG8_LAS unsigned*)(lds + (bufoff) + ldsw + _i * 8192), 16, 0, 0); } while (0)
; #define PG8_LDA(dst, b, h) do { _Pragma("unroll") for (int m = 0; m < 4; ++m) _Pragma("unroll") for (int k = 0; k < 2; ++k) dst[m][k] = *(const PG8_LAS bf16x8*)(lds + PG8_SA(b, h) + aoff + m * 2048 + k * 1024); } while (0)
; #define PG8_LDB(dst, b, h) do { _Pragma("unroll") for (int n = 0; n < 2; ++n) _Pragma("unroll") for (int k = 0; k < 2; ++k) dst[n][k] = *(const PG8_LAS bf16x8*)(lds + PG8_SB(b, h) + boff + n * 2048 + k * 1024); } while (0)
; #define PG8_MMA(ai, bj, At, Bt) do { __builtin_amdgcn_s_setprio(1); _Pragma("unroll") for (int m = 0; m < 4; ++m) _Pragma("unroll") for (int n = 0; n < 2; ++n) _Pragma("unroll") for (int k = 0; k < 2; ++k) \
;         acc[ai][bj][m][n] = __builtin_amdgcn_mfma_f32_16x16x32_bf16(Bt[n][k], At[m][k], acc[ai][bj][m][n], 0, 0, 0); __builtin_amdgcn_s_setprio(0); } while (0)
; #define PG8_WAIT_V(n) asm volatile("s_waitcnt vmcnt(" #n ")" ::: "memory")
; #define PG8_WAIT_L(n) asm volatile("s_waitcnt lgkmcnt(" #n ")" ::: "memory")
; #define PG8_BAR __builtin_amdgcn_s_barrier()
; #define PG8_SCHED __builtin_amdgcn_sched_barrier(0)
; template <class Epi, class Sched, bool ALIGN_EPI, int LMASK = -1, int LMASKB = LMASK>
; __device__ __forceinline__ void gemm_phase(PG8_LAS unsigned char* lds, const Gemm g, const Sched& S, const Epi& E) {
;     ...
;             PG8_WAIT_V(8); PG8_WAIT_L(0); PG8_BAR; PG8_MMA(1, 0, At, B0); PG8_MMA(1, 1, At, B1); PG8_BAR; PG8_SCHED;
;             PG8_LDB(B0, 1, 0); PG8_LDB(B1, 1, 1); PG8_SCHED; PG8_LDA(At, 1, 0); PG8_STAGE(PG8_SA(0, 1), a2 + hstepA, voffA);
;             PG8_WAIT_V(8); PG8_WAIT_L(0); PG8_BAR; PG8_MMA(0, 0, At, B0); PG8_MMA(0, 1, At, B1); PG8_BAR; PG8_SCHED;
	v_mfma_f32_16x16x32_bf16 v[62:65], v[130:133], v[188:191], v[62:65]
	v_mfma_f32_16x16x32_bf16 v[58:61], v[152:155], v[188:191], v[58:61]
	v_mfma_f32_16x16x32_bf16 v[46:49], v[130:133], v[218:221], v[46:49]
	v_mfma_f32_16x16x32_bf16 v[42:45], v[152:155], v[218:221], v[42:45]
	v_mfma_f32_16x16x32_bf16 v[30:33], v[130:133], v[226:229], v[30:33]
	v_mfma_f32_16x16x32_bf16 v[26:29], v[152:155], v[226:229], v[26:29]
	v_mfma_f32_16x16x32_bf16 v[14:17], v[130:133], v[234:237], v[14:17]
	v_mfma_f32_16x16x32_bf16 v[10:13], v[152:155], v[234:237], v[10:13]
	v_mfma_f32_16x16x32_bf16 v[62:65], v[142:145], v[206:209], v[62:65]
	v_mfma_f32_16x16x32_bf16 v[58:61], v[156:159], v[206:209], v[58:61]
	v_mfma_f32_16x16x32_bf16 v[46:49], v[142:145], v[222:225], v[46:49]
	v_mfma_f32_16x16x32_bf16 v[42:45], v[156:159], v[222:225], v[42:45]
	v_mfma_f32_16x16x32_bf16 v[30:33], v[142:145], v[230:233], v[30:33]
	v_mfma_f32_16x16x32_bf16 v[26:29], v[156:159], v[230:233], v[26:29]
	v_mfma_f32_16x16x32_bf16 v[14:17], v[142:145], v[238:241], v[14:17]
	v_mfma_f32_16x16x32_bf16 v[10:13], v[156:159], v[238:241], v[10:13]
	v_mfma_f32_16x16x32_bf16 v[54:57], v[160:163], v[188:191], v[54:57]
	v_mfma_f32_16x16x32_bf16 v[50:53], v[168:171], v[188:191], v[50:53]
	v_mfma_f32_16x16x32_bf16 v[38:41], v[160:163], v[218:221], v[38:41]
	v_mfma_f32_16x16x32_bf16 v[34:37], v[168:171], v[218:221], v[34:37]
	v_mfma_f32_16x16x32_bf16 v[22:25], v[160:163], v[226:229], v[22:25]
	v_mfma_f32_16x16x32_bf16 v[18:21], v[168:171], v[226:229], v[18:21]
	v_mfma_f32_16x16x32_bf16 v[6:9], v[160:163], v[234:237], v[6:9]
	v_mfma_f32_16x16x32_bf16 v[2:5], v[168:171], v[234:237], v[2:5]
	v_mfma_f32_16x16x32_bf16 v[54:57], v[164:167], v[206:209], v[54:57]
	v_mfma_f32_16x16x32_bf16 v[50:53], v[172:175], v[206:209], v[50:53]
	v_mfma_f32_16x16x32_bf16 v[38:41], v[164:167], v[222:225], v[38:41]
	v_mfma_f32_16x16x32_bf16 v[34:37], v[172:175], v[222:225], v[34:37]
	v_mfma_f32_16x16x32_bf16 v[22:25], v[164:167], v[230:233], v[22:25]
	v_mfma_f32_16x16x32_bf16 v[18:21], v[172:175], v[230:233], v[18:21]
	v_mfma_f32_16x16x32_bf16 v[6:9], v[164:167], v[238:241], v[6:9]
	v_mfma_f32_16x16x32_bf16 v[2:5], v[172:175], v[238:241], v[2:5]
	s_barrier
	s_setprio 0
	s_add_i32 s51, 0, 0x18000
	s_add_i32 s52, 0, 0x1c000
	v_add_u32_e32 v156, s51, v149
	v_add_u32_e32 v172, s52, v149
	ds_read_b128 v[130:133], v156
	ds_read_b128 v[142:145], v156 offset:1024
	ds_read_b128 v[152:155], v156 offset:2048
	ds_read_b128 v[156:159], v156 offset:3072
	ds_read_b128 v[160:163], v172
	ds_read_b128 v[164:167], v172 offset:1024
	ds_read_b128 v[168:171], v172 offset:2048
	ds_read_b128 v[172:175], v172 offset:3072
	s_add_u32 s30, s30, 0x400000
	s_addc_u32 s31, s31, 0
	s_mov_b32 m0, s39
	v_lshl_add_u64 v[212:213], s[30:31], 0, v[134:135]
	ds_read_b128 v[188:191], v151 offset:32768
	ds_read_b128 v[206:209], v151 offset:33792
	ds_read_b128 v[218:221], v151 offset:34816
	ds_read_b128 v[222:225], v151 offset:35840
	ds_read_b128 v[226:229], v151 offset:36864
	ds_read_b128 v[230:233], v151 offset:37888
	ds_read_b128 v[234:237], v151 offset:38912
	ds_read_b128 v[238:241], v151 offset:39936
	global_load_lds_dwordx4 v[212:213], off
	s_mov_b32 m0, s40
	v_lshl_add_u64 v[212:213], s[30:31], 0, v[136:137]
	global_load_lds_dwordx4 v[212:213], off
	s_setprio 1
	s_waitcnt vmcnt(8) lgkmcnt(0)
	s_barrier
	v_mfma_f32_16x16x32_bf16 v[126:129], v[130:133], v[188:191], v[126:129]
	v_mfma_f32_16x16x32_bf16 v[122:125], v[152:155], v[188:191], v[122:125]
	v_mfma_f32_16x16x32_bf16 v[110:113], v[130:133], v[218:221], v[110:113]
	v_mfma_f32_16x16x32_bf16 v[106:109], v[152:155], v[218:221], v[106:109]
	v_mfma_f32_16x16x32_bf16 v[94:97], v[130:133], v[226:229], v[94:97]
	v_mfma_f32_16x16x32_bf16 v[90:93], v[152:155], v[226:229], v[90:93]
	v_mfma_f32_16x16x32_bf16 v[78:81], v[130:133], v[234:237], v[78:81]
	v_mfma_f32_16x16x32_bf16 v[74:77], v[152:155], v[234:237], v[74:77]
	v_mfma_f32_16x16x32_bf16 v[126:129], v[142:145], v[206:209], v[126:129]
	v_mfma_f32_16x16x32_bf16 v[122:125], v[156:159], v[206:209], v[122:125]
	v_mfma_f32_16x16x32_bf16 v[110:113], v[142:145], v[222:225], v[110:113]
	v_mfma_f32_16x16x32_bf16 v[106:109], v[156:159], v[222:225], v[106:109]
	v_mfma_f32_16x16x32_bf16 v[94:97], v[142:145], v[230:233], v[94:97]
	v_mfma_f32_16x16x32_bf16 v[90:93], v[156:159], v[230:233], v[90:93]
	v_mfma_f32_16x16x32_bf16 v[78:81], v[142:145], v[238:241], v[78:81]
	v_mfma_f32_16x16x32_bf16 v[74:77], v[156:159], v[238:241], v[74:77]
	v_mfma_f32_16x16x32_bf16 v[118:121], v[160:163], v[188:191], v[118:121]
	v_mfma_f32_16x16x32_bf16 v[114:117], v[168:171], v[188:191], v[114:117]
	v_mfma_f32_16x16x32_bf16 v[102:105], v[160:163], v[218:221], v[102:105]
	v_mfma_f32_16x16x32_bf16 v[98:101], v[168:171], v[218:221], v[98:101]
	v_mfma_f32_16x16x32_bf16 v[86:89], v[160:163], v[226:229], v[86:89]
	v_mfma_f32_16x16x32_bf16 v[82:85], v[168:171], v[226:229], v[82:85]
	v_mfma_f32_16x16x32_bf16 v[70:73], v[160:163], v[234:237], v[70:73]
	v_mfma_f32_16x16x32_bf16 v[66:69], v[168:171], v[234:237], v[66:69]
	v_mfma_f32_16x16x32_bf16 v[118:121], v[164:167], v[206:209], v[118:121]
	v_mfma_f32_16x16x32_bf16 v[114:117], v[172:175], v[206:209], v[114:117]
	v_mfma_f32_16x16x32_bf16 v[102:105], v[164:167], v[222:225], v[102:105]
	v_mfma_f32_16x16x32_bf16 v[98:101], v[172:175], v[222:225], v[98:101]
	v_mfma_f32_16x16x32_bf16 v[86:89], v[164:167], v[230:233], v[86:89]
	v_mfma_f32_16x16x32_bf16 v[82:85], v[172:175], v[230:233], v[82:85]
	v_mfma_f32_16x16x32_bf16 v[70:73], v[164:167], v[238:241], v[70:73]
	v_mfma_f32_16x16x32_bf16 v[66:69], v[172:175], v[238:241], v[66:69]
	s_barrier
; #define PG8_STAGE(bufoff, gbase, voff) do { _Pragma("unroll") for (int _i = 0; _i < 2; ++_i) \
;         __builtin_amdgcn_global_load_lds((const unsigned*)((const char*)(gbase) + (voff)[_i]), (PG8_LAS unsigned*)(lds + (bufoff) + ldsw + _i * 8192), 16, 0, 0); } while (0)
; #define PG8_LDA(dst, b, h) do { _Pragma("unroll") for (int m = 0; m < 4; ++m) _Pragma("unroll") for (int k = 0; k < 2; ++k) dst[m][k] = *(const PG8_LAS bf16x8*)(lds + PG8_SA(b, h) + aoff + m * 2048 + k * 1024); } while (0)
; #define PG8_MMA(ai, bj, At, Bt) do { __builtin_amdgcn_s_setprio(1); _Pragma("unroll") for (int m = 0; m < 4; ++m) _Pragma("unroll") for (int n = 0; n < 2; ++n) _Pragma("unroll") for (int k = 0; k < 2; ++k) \
;         acc[ai][bj][m][n] = __builtin_amdgcn_mfma_f32_16x16x32_bf16(Bt[n][k], At[m][k], acc[ai][bj][m][n], 0, 0, 0); __builtin_amdgcn_s_setprio(0); } while (0)
; #define PG8_WAIT_V(n) asm volatile("s_waitcnt vmcnt(" #n ")" ::: "memory")
; #define PG8_WAIT_L(n) asm volatile("s_waitcnt lgkmcnt(" #n ")" ::: "memory")
; #define PG8_BAR __builtin_amdgcn_s_barrier()
; #define PG8_SCHED __builtin_amdgcn_sched_barrier(0)
; template <class Epi, class Sched, bool ALIGN_EPI, int LMASK = -1, int LMASKB = LMASK>
; __device__ __forceinline__ void gemm_phase(PG8_LAS unsigned char* lds, const Gemm g, const Sched& S, const Epi& E) {
;     ...
;             PG8_LDA(At, 1, 1); PG8_STAGE(PG8_SB(1, 0), b3, voffB); PG8_STAGE(PG8_SB(1, 1), b3 + hstepB, voffB); PG8_STAGE(PG8_SA(1, 0), a3, voffA);
;             PG8_WAIT_V(8); PG8_WAIT_L(0); PG8_BAR; PG8_MMA(1, 0, At, B0); PG8_MMA(1, 1, At, B1); PG8_BAR; PG8_SCHED;
;         }
;         if constexpr (ALIGN_EPI) { if (wr == 0) PG8_BAR; }
	s_setprio 0
	s_add_i32 s30, s51, s38
	v_lshl_add_u64 v[146:147], v[146:147], 0, s[80:81]
	s_mov_b32 m0, s30
	ds_read_b128 v[188:191], v151 offset:49152
	ds_read_b128 v[206:209], v151 offset:50176
	ds_read_b128 v[218:221], v151 offset:51200
	ds_read_b128 v[222:225], v151 offset:52224
	ds_read_b128 v[226:229], v151 offset:53248
	ds_read_b128 v[230:233], v151 offset:54272
	ds_read_b128 v[234:237], v151 offset:55296
	ds_read_b128 v[238:241], v151 offset:56320
	global_load_lds_dwordx4 v[146:147], off
	s_add_i32 m0, s30, 0x2000
	s_add_u32 s2, s2, 0x400800
	v_lshl_add_u64 v[146:147], v[176:177], 0, s[80:81]
	s_addc_u32 s3, s3, 0
	s_add_i32 s30, s52, s38
	global_load_lds_dwordx4 v[146:147], off
	s_mov_b32 m0, s30
	v_lshl_add_u64 v[146:147], s[2:3], 0, v[134:135]
	global_load_lds_dwordx4 v[146:147], off
	s_add_i32 m0, s30, 0x2000
	v_lshl_add_u64 v[146:147], s[2:3], 0, v[136:137]
	global_load_lds_dwordx4 v[146:147], off
	s_mov_b32 m0, s41
	v_lshl_add_u64 v[146:147], v[194:195], 0, s[80:81]
	global_load_lds_dwordx4 v[146:147], off
	s_mov_b32 m0, s42
	v_lshl_add_u64 v[146:147], v[210:211], 0, s[80:81]
	global_load_lds_dwordx4 v[146:147], off
	s_setprio 1
	s_waitcnt vmcnt(8) lgkmcnt(0)
	s_barrier
	v_mfma_f32_16x16x32_bf16 v[62:65], v[130:133], v[188:191], v[62:65]
	v_mfma_f32_16x16x32_bf16 v[58:61], v[152:155], v[188:191], v[58:61]
	v_mfma_f32_16x16x32_bf16 v[46:49], v[130:133], v[218:221], v[46:49]
	v_mfma_f32_16x16x32_bf16 v[42:45], v[152:155], v[218:221], v[42:45]
	v_mfma_f32_16x16x32_bf16 v[30:33], v[130:133], v[226:229], v[30:33]
	v_mfma_f32_16x16x32_bf16 v[26:29], v[152:155], v[226:229], v[26:29]
	v_mfma_f32_16x16x32_bf16 v[14:17], v[130:133], v[234:237], v[14:17]
	v_mfma_f32_16x16x32_bf16 v[10:13], v[152:155], v[234:237], v[10:13]
	v_mfma_f32_16x16x32_bf16 v[62:65], v[142:145], v[206:209], v[62:65]
	v_mfma_f32_16x16x32_bf16 v[58:61], v[156:159], v[206:209], v[58:61]
	v_mfma_f32_16x16x32_bf16 v[46:49], v[142:145], v[222:225], v[46:49]
	v_mfma_f32_16x16x32_bf16 v[42:45], v[156:159], v[222:225], v[42:45]
	v_mfma_f32_16x16x32_bf16 v[30:33], v[142:145], v[230:233], v[30:33]
	v_mfma_f32_16x16x32_bf16 v[26:29], v[156:159], v[230:233], v[26:29]
	v_mfma_f32_16x16x32_bf16 v[14:17], v[142:145], v[238:241], v[14:17]
	v_mfma_f32_16x16x32_bf16 v[10:13], v[156:159], v[238:241], v[10:13]
	v_mfma_f32_16x16x32_bf16 v[54:57], v[160:163], v[188:191], v[54:57]
	v_mfma_f32_16x16x32_bf16 v[50:53], v[168:171], v[188:191], v[50:53]
	v_mfma_f32_16x16x32_bf16 v[38:41], v[160:163], v[218:221], v[38:41]
	v_mfma_f32_16x16x32_bf16 v[34:37], v[168:171], v[218:221], v[34:37]
	v_mfma_f32_16x16x32_bf16 v[22:25], v[160:163], v[226:229], v[22:25]
	v_mfma_f32_16x16x32_bf16 v[18:21], v[168:171], v[226:229], v[18:21]
	v_mfma_f32_16x16x32_bf16 v[6:9], v[160:163], v[234:237], v[6:9]
	v_mfma_f32_16x16x32_bf16 v[2:5], v[168:171], v[234:237], v[2:5]
	v_mfma_f32_16x16x32_bf16 v[54:57], v[164:167], v[206:209], v[54:57]
	v_mfma_f32_16x16x32_bf16 v[50:53], v[172:175], v[206:209], v[50:53]
	v_mfma_f32_16x16x32_bf16 v[38:41], v[164:167], v[222:225], v[38:41]
	v_mfma_f32_16x16x32_bf16 v[34:37], v[172:175], v[222:225], v[34:37]
	v_mfma_f32_16x16x32_bf16 v[22:25], v[164:167], v[230:233], v[22:25]
	v_mfma_f32_16x16x32_bf16 v[18:21], v[172:175], v[230:233], v[18:21]
	v_mfma_f32_16x16x32_bf16 v[6:9], v[164:167], v[238:241], v[6:9]
	v_mfma_f32_16x16x32_bf16 v[2:5], v[172:175], v[238:241], v[2:5]
	s_barrier
	s_setprio 0
	s_add_i32 s50, s50, 2
	s_add_u32 s28, s28, 0x1000
	s_addc_u32 s29, s29, 0
	s_add_u32 s48, s48, 0x1000
	s_addc_u32 s49, s49, 0
	s_cmpk_gt_u32 s50, 0xfd
	s_cbranch_scc0 .LBB0_761
	s_and_b64 vcc, exec, s[14:15]
	s_cbranch_vccz .LBB0_764
	s_barrier
